# stack11 + loop-edge edit in the 5 GEMM K-loops: counter/pointer SALU moved ahead of the loop-back barrier, head pointer SALU moved after the first ds_read group
# baseline (speedup 1.0000x reference)
; #define PG8_STAGE(bufoff, gbase, voff) do { _Pragma("unroll") for (int _i = 0; _i < 2; ++_i) \
;         __builtin_amdgcn_global_load_lds((const unsigned*)((const char*)(gbase) + (voff)[_i]), (PG8_LAS unsigned*)(lds + (bufoff) + ldsw + _i * 8192), 16, 0, 0); } while (0)
; #define PG8_LDA(dst, b, h) do { _Pragma("unroll") for (int m = 0; m < 4; ++m) _Pragma("unroll") for (int k = 0; k < 2; ++k) dst[m][k] = *(const PG8_LAS bf16x8*)(lds + PG8_SA(b, h) + aoff + m * 2048 + k * 1024); } while (0)
; #define PG8_LDB(dst, b, h) do { _Pragma("unroll") for (int n = 0; n < 2; ++n) _Pragma("unroll") for (int k = 0; k < 2; ++k) dst[n][k] = *(const PG8_LAS bf16x8*)(lds + PG8_SB(b, h) + boff + n * 2048 + k * 1024); } while (0)
; #define PG8_MMA(ai, bj, At, Bt) do { __builtin_amdgcn_s_setprio(1); _Pragma("unroll") for (int m = 0; m < 4; ++m) _Pragma("unroll") for (int n = 0; n < 2; ++n) _Pragma("unroll") for (int k = 0; k < 2; ++k) \
;         acc[ai][bj][m][n] = __builtin_amdgcn_mfma_f32_16x16x32_bf16(Bt[n][k], At[m][k], acc[ai][bj][m][n], 0, 0, 0); __builtin_amdgcn_s_setprio(0); } while (0)
; #define PG8_WAIT_V(n) asm volatile("s_waitcnt vmcnt(" #n ")" ::: "memory")
; #define PG8_WAIT_L(n) asm volatile("s_waitcnt lgkmcnt(" #n ")" ::: "memory")
; #define PG8_BAR __builtin_amdgcn_s_barrier()
; #define PG8_SCHED __builtin_amdgcn_sched_barrier(0)
; template <class Epi, class Sched, bool ALIGN_EPI = false, bool SP2 = false>
; __device__ __forceinline__ void gemm_phase(PG8_LAS unsigned char* lds, const Gemm g, const Sched& S, const Epi& E, int wave0) {
;     ...
;             PG8_LDB(B0, 0, 0); PG8_LDB(B1, 0, 1); PG8_SCHED; PG8_LDA(At, 0, 0); PG8_STAGE(PG8_SA(1, 1), a1 + hstep, voffA);
;             PG8_WAIT_V(8); PG8_WAIT_L(0); PG8_BAR; PG8_MMA(0, 0, At, B0); PG8_MMA(0, 1, At, B1); PG8_BAR; PG8_SCHED;
;             PG8_LDA(At, 0, 1); PG8_STAGE(PG8_SB(0, 0), b2, voffB); PG8_STAGE(PG8_SB(0, 1), b2 + hstep, voffB); PG8_STAGE(PG8_SA(0, 0), a2, voffA);
;             PG8_WAIT_V(8); PG8_WAIT_L(0); PG8_BAR; PG8_MMA(1, 0, At, B0); PG8_MMA(1, 1, At, B1); PG8_BAR; PG8_SCHED;
.LBB0_195:
	s_add_i32 s86, 0, 0x10000
	v_add_u32_e32 v0, s86, v174
	ds_read_b128 v[130:133], v0
	ds_read_b128 v[134:137], v0 offset:1024
	ds_read_b128 v[138:141], v0 offset:2048
	ds_read_b128 v[142:145], v0 offset:3072
	s_add_u32 s4, s0, 0xfffc0080
	s_addc_u32 s5, s1, -1
	s_cmp_eq_u32 s85, 12
	s_cselect_b32 s43, s44, s5
	s_cselect_b32 s42, s53, s4
	s_cselect_b32 s5, s51, s84
	s_cselect_b32 s4, s82, s83
	s_add_i32 s88, 0, 0x14000
	v_add_u32_e32 v0, s88, v174
	s_waitcnt lgkmcnt(0)
	ds_read_b128 v[158:161], v0
	ds_read_b128 v[162:165], v0 offset:1024
	ds_read_b128 v[166:169], v0 offset:2048
	ds_read_b128 v[170:173], v0 offset:3072
	v_lshl_add_u64 v[208:209], s[0:1], 0, v[154:155]
	s_add_i32 m0, s62, 0xc000
	ds_read_b128 v[176:179], v175
	ds_read_b128 v[180:183], v175 offset:1024
	ds_read_b128 v[184:187], v175 offset:2048
	ds_read_b128 v[188:191], v175 offset:3072
	ds_read_b128 v[192:195], v175 offset:4096
	ds_read_b128 v[196:199], v175 offset:5120
	ds_read_b128 v[200:203], v175 offset:6144
	ds_read_b128 v[204:207], v175 offset:7168
	global_load_lds_dwordx4 v[208:209], off
	v_lshl_add_u64 v[208:209], s[0:1], 0, v[156:157]
	s_add_i32 m0, s62, 0xe000
	s_nop 0
	global_load_lds_dwordx4 v[208:209], off
	s_waitcnt vmcnt(8)
	s_waitcnt lgkmcnt(0)
	s_barrier
	s_setprio 1
	s_waitcnt lgkmcnt(0)
	v_mfma_f32_16x16x32_bf16 v[126:129], v[130:133], v[176:179], v[126:129]
	v_mfma_f32_16x16x32_bf16 v[122:125], v[138:141], v[176:179], v[122:125]
	v_mfma_f32_16x16x32_bf16 v[110:113], v[130:133], v[184:187], v[110:113]
	v_mfma_f32_16x16x32_bf16 v[106:109], v[138:141], v[184:187], v[106:109]
	v_mfma_f32_16x16x32_bf16 v[94:97], v[130:133], v[192:195], v[94:97]
	v_mfma_f32_16x16x32_bf16 v[90:93], v[138:141], v[192:195], v[90:93]
	v_mfma_f32_16x16x32_bf16 v[78:81], v[130:133], v[200:203], v[78:81]
	v_mfma_f32_16x16x32_bf16 v[74:77], v[138:141], v[200:203], v[74:77]
	v_mfma_f32_16x16x32_bf16 v[126:129], v[134:137], v[180:183], v[126:129]
	v_mfma_f32_16x16x32_bf16 v[122:125], v[142:145], v[180:183], v[122:125]
	v_mfma_f32_16x16x32_bf16 v[110:113], v[134:137], v[188:191], v[110:113]
	v_mfma_f32_16x16x32_bf16 v[106:109], v[142:145], v[188:191], v[106:109]
	v_mfma_f32_16x16x32_bf16 v[94:97], v[134:137], v[196:199], v[94:97]
	v_mfma_f32_16x16x32_bf16 v[90:93], v[142:145], v[196:199], v[90:93]
	v_mfma_f32_16x16x32_bf16 v[78:81], v[134:137], v[204:207], v[78:81]
	v_mfma_f32_16x16x32_bf16 v[74:77], v[142:145], v[204:207], v[74:77]
	s_setprio 0
	s_setprio 1
	v_mfma_f32_16x16x32_bf16 v[118:121], v[158:161], v[176:179], v[118:121]
	v_mfma_f32_16x16x32_bf16 v[114:117], v[166:169], v[176:179], v[114:117]
	v_mfma_f32_16x16x32_bf16 v[102:105], v[158:161], v[184:187], v[102:105]
	v_mfma_f32_16x16x32_bf16 v[98:101], v[166:169], v[184:187], v[98:101]
	v_mfma_f32_16x16x32_bf16 v[86:89], v[158:161], v[192:195], v[86:89]
	v_mfma_f32_16x16x32_bf16 v[82:85], v[166:169], v[192:195], v[82:85]
	v_mfma_f32_16x16x32_bf16 v[70:73], v[158:161], v[200:203], v[70:73]
	v_mfma_f32_16x16x32_bf16 v[66:69], v[166:169], v[200:203], v[66:69]
	v_mfma_f32_16x16x32_bf16 v[118:121], v[162:165], v[180:183], v[118:121]
	v_mfma_f32_16x16x32_bf16 v[114:117], v[170:173], v[180:183], v[114:117]
	v_mfma_f32_16x16x32_bf16 v[102:105], v[162:165], v[188:191], v[102:105]
	v_mfma_f32_16x16x32_bf16 v[98:101], v[170:173], v[188:191], v[98:101]
	v_mfma_f32_16x16x32_bf16 v[86:89], v[162:165], v[196:199], v[86:89]
	v_mfma_f32_16x16x32_bf16 v[82:85], v[170:173], v[196:199], v[82:85]
	v_mfma_f32_16x16x32_bf16 v[70:73], v[162:165], v[204:207], v[70:73]
	v_mfma_f32_16x16x32_bf16 v[66:69], v[170:173], v[204:207], v[66:69]
	s_setprio 0
	s_barrier
	s_add_i32 s86, s86, s61
	v_lshl_add_u64 v[208:209], s[4:5], 0, v[150:151]
	s_mov_b32 m0, s86
	ds_read_b128 v[176:179], v175 offset:16384
	ds_read_b128 v[180:183], v175 offset:17408
	ds_read_b128 v[184:187], v175 offset:18432
	ds_read_b128 v[188:191], v175 offset:19456
	ds_read_b128 v[192:195], v175 offset:20480
	ds_read_b128 v[196:199], v175 offset:21504
	ds_read_b128 v[200:203], v175 offset:22528
	ds_read_b128 v[204:207], v175 offset:23552
	global_load_lds_dwordx4 v[208:209], off
	s_add_i32 m0, s86, 0x2000
	s_add_u32 s86, s4, 0x40000
	v_lshl_add_u64 v[210:211], s[4:5], 0, v[146:147]
	s_addc_u32 s87, s5, 0
	s_add_i32 s88, s88, s61
	global_load_lds_dwordx4 v[210:211], off
	v_lshl_add_u64 v[212:213], s[86:87], 0, v[150:151]
	s_mov_b32 m0, s88
	v_lshl_add_u64 v[214:215], s[42:43], 0, v[148:149]
	global_load_lds_dwordx4 v[212:213], off
	v_lshl_add_u64 v[212:213], s[86:87], 0, v[146:147]
	s_add_i32 m0, s88, 0x2000
	s_nop 0
	global_load_lds_dwordx4 v[212:213], off
	v_lshl_add_u64 v[212:213], s[42:43], 0, v[152:153]
	s_mov_b32 m0, s62
	s_nop 0
	global_load_lds_dwordx4 v[212:213], off
	s_mov_b32 m0, s63
	s_nop 0
	global_load_lds_dwordx4 v[214:215], off
	s_waitcnt vmcnt(8)
	s_waitcnt lgkmcnt(0)
	s_barrier
; #define PG8_STAGE(bufoff, gbase, voff) do { _Pragma("unroll") for (int _i = 0; _i < 2; ++_i) \
;         __builtin_amdgcn_global_load_lds((const unsigned*)((const char*)(gbase) + (voff)[_i]), (PG8_LAS unsigned*)(lds + (bufoff) + ldsw + _i * 8192), 16, 0, 0); } while (0)
; #define PG8_LDA(dst, b, h) do { _Pragma("unroll") for (int m = 0; m < 4; ++m) _Pragma("unroll") for (int k = 0; k < 2; ++k) dst[m][k] = *(const PG8_LAS bf16x8*)(lds + PG8_SA(b, h) + aoff + m * 2048 + k * 1024); } while (0)
; #define PG8_LDB(dst, b, h) do { _Pragma("unroll") for (int n = 0; n < 2; ++n) _Pragma("unroll") for (int k = 0; k < 2; ++k) dst[n][k] = *(const PG8_LAS bf16x8*)(lds + PG8_SB(b, h) + boff + n * 2048 + k * 1024); } while (0)
; #define PG8_MMA(ai, bj, At, Bt) do { __builtin_amdgcn_s_setprio(1); _Pragma("unroll") for (int m = 0; m < 4; ++m) _Pragma("unroll") for (int n = 0; n < 2; ++n) _Pragma("unroll") for (int k = 0; k < 2; ++k) \
;         acc[ai][bj][m][n] = __builtin_amdgcn_mfma_f32_16x16x32_bf16(Bt[n][k], At[m][k], acc[ai][bj][m][n], 0, 0, 0); __builtin_amdgcn_s_setprio(0); } while (0)
; #define PG8_WAIT_V(n) asm volatile("s_waitcnt vmcnt(" #n ")" ::: "memory")
; #define PG8_WAIT_L(n) asm volatile("s_waitcnt lgkmcnt(" #n ")" ::: "memory")
; #define PG8_BAR __builtin_amdgcn_s_barrier()
; #define PG8_SCHED __builtin_amdgcn_sched_barrier(0)
; template <class Epi, class Sched, bool ALIGN_EPI = false, bool SP2 = false>
; __device__ __forceinline__ void gemm_phase(PG8_LAS unsigned char* lds, const Gemm g, const Sched& S, const Epi& E, int wave0) {
;     ...
;             PG8_WAIT_V(8); PG8_WAIT_L(0); PG8_BAR; PG8_MMA(1, 0, At, B0); PG8_MMA(1, 1, At, B1); PG8_BAR; PG8_SCHED;
;             PG8_LDB(B0, 1, 0); PG8_LDB(B1, 1, 1); PG8_SCHED; PG8_LDA(At, 1, 0); PG8_STAGE(PG8_SA(0, 1), a2 + hstep, voffA);
;             PG8_WAIT_V(8); PG8_WAIT_L(0); PG8_BAR; PG8_MMA(0, 0, At, B0); PG8_MMA(0, 1, At, B1); PG8_BAR; PG8_SCHED;
	s_setprio 1
	s_waitcnt lgkmcnt(0)
	v_mfma_f32_16x16x32_bf16 v[62:65], v[130:133], v[176:179], v[62:65]
	v_mfma_f32_16x16x32_bf16 v[58:61], v[138:141], v[176:179], v[58:61]
	v_mfma_f32_16x16x32_bf16 v[46:49], v[130:133], v[184:187], v[46:49]
	v_mfma_f32_16x16x32_bf16 v[42:45], v[138:141], v[184:187], v[42:45]
	v_mfma_f32_16x16x32_bf16 v[30:33], v[130:133], v[192:195], v[30:33]
	v_mfma_f32_16x16x32_bf16 v[26:29], v[138:141], v[192:195], v[26:29]
	v_mfma_f32_16x16x32_bf16 v[14:17], v[130:133], v[200:203], v[14:17]
	v_mfma_f32_16x16x32_bf16 v[10:13], v[138:141], v[200:203], v[10:13]
	v_mfma_f32_16x16x32_bf16 v[62:65], v[134:137], v[180:183], v[62:65]
	v_mfma_f32_16x16x32_bf16 v[58:61], v[142:145], v[180:183], v[58:61]
	v_mfma_f32_16x16x32_bf16 v[46:49], v[134:137], v[188:191], v[46:49]
	v_mfma_f32_16x16x32_bf16 v[42:45], v[142:145], v[188:191], v[42:45]
	v_mfma_f32_16x16x32_bf16 v[30:33], v[134:137], v[196:199], v[30:33]
	v_mfma_f32_16x16x32_bf16 v[26:29], v[142:145], v[196:199], v[26:29]
	v_mfma_f32_16x16x32_bf16 v[14:17], v[134:137], v[204:207], v[14:17]
	v_mfma_f32_16x16x32_bf16 v[10:13], v[142:145], v[204:207], v[10:13]
	s_setprio 0
	s_setprio 1
	v_mfma_f32_16x16x32_bf16 v[54:57], v[158:161], v[176:179], v[54:57]
	v_mfma_f32_16x16x32_bf16 v[50:53], v[166:169], v[176:179], v[50:53]
	v_mfma_f32_16x16x32_bf16 v[38:41], v[158:161], v[184:187], v[38:41]
	v_mfma_f32_16x16x32_bf16 v[34:37], v[166:169], v[184:187], v[34:37]
	v_mfma_f32_16x16x32_bf16 v[22:25], v[158:161], v[192:195], v[22:25]
	v_mfma_f32_16x16x32_bf16 v[18:21], v[166:169], v[192:195], v[18:21]
	v_mfma_f32_16x16x32_bf16 v[6:9], v[158:161], v[200:203], v[6:9]
	v_mfma_f32_16x16x32_bf16 v[2:5], v[166:169], v[200:203], v[2:5]
	v_mfma_f32_16x16x32_bf16 v[54:57], v[162:165], v[180:183], v[54:57]
	v_mfma_f32_16x16x32_bf16 v[50:53], v[170:173], v[180:183], v[50:53]
	v_mfma_f32_16x16x32_bf16 v[38:41], v[162:165], v[188:191], v[38:41]
	v_mfma_f32_16x16x32_bf16 v[34:37], v[170:173], v[188:191], v[34:37]
	v_mfma_f32_16x16x32_bf16 v[22:25], v[162:165], v[196:199], v[22:25]
	v_mfma_f32_16x16x32_bf16 v[18:21], v[170:173], v[196:199], v[18:21]
	v_mfma_f32_16x16x32_bf16 v[6:9], v[162:165], v[204:207], v[6:9]
	v_mfma_f32_16x16x32_bf16 v[2:5], v[170:173], v[204:207], v[2:5]
	s_setprio 0
	s_barrier
	s_add_i32 s86, 0, 0x18000
	v_add_u32_e32 v0, s86, v174
	s_add_i32 s87, 0, 0x1c000
	ds_read_b128 v[130:133], v0
	ds_read_b128 v[134:137], v0 offset:1024
	ds_read_b128 v[138:141], v0 offset:2048
	ds_read_b128 v[142:145], v0 offset:3072
	v_add_u32_e32 v0, s87, v174
	ds_read_b128 v[158:161], v0
	ds_read_b128 v[162:165], v0 offset:1024
	ds_read_b128 v[166:169], v0 offset:2048
	ds_read_b128 v[170:173], v0 offset:3072
	s_add_u32 s42, s42, 0x40000
	s_addc_u32 s43, s43, 0
	s_mov_b32 m0, s64
	v_lshl_add_u64 v[216:217], s[42:43], 0, v[152:153]
	ds_read_b128 v[176:179], v175 offset:32768
	ds_read_b128 v[180:183], v175 offset:33792
	ds_read_b128 v[184:187], v175 offset:34816
	ds_read_b128 v[188:191], v175 offset:35840
	ds_read_b128 v[192:195], v175 offset:36864
	ds_read_b128 v[196:199], v175 offset:37888
	ds_read_b128 v[200:203], v175 offset:38912
	ds_read_b128 v[204:207], v175 offset:39936
	global_load_lds_dwordx4 v[216:217], off
	v_lshl_add_u64 v[216:217], s[42:43], 0, v[148:149]
	s_mov_b32 m0, s65
	s_nop 0
	global_load_lds_dwordx4 v[216:217], off
	s_waitcnt vmcnt(8)
	s_waitcnt lgkmcnt(0)
	s_barrier
	s_setprio 1
	s_waitcnt lgkmcnt(0)
	v_mfma_f32_16x16x32_bf16 v[126:129], v[130:133], v[176:179], v[126:129]
	v_mfma_f32_16x16x32_bf16 v[122:125], v[138:141], v[176:179], v[122:125]
	v_mfma_f32_16x16x32_bf16 v[110:113], v[130:133], v[184:187], v[110:113]
	v_mfma_f32_16x16x32_bf16 v[106:109], v[138:141], v[184:187], v[106:109]
	v_mfma_f32_16x16x32_bf16 v[94:97], v[130:133], v[192:195], v[94:97]
	v_mfma_f32_16x16x32_bf16 v[90:93], v[138:141], v[192:195], v[90:93]
	v_mfma_f32_16x16x32_bf16 v[78:81], v[130:133], v[200:203], v[78:81]
	v_mfma_f32_16x16x32_bf16 v[74:77], v[138:141], v[200:203], v[74:77]
	v_mfma_f32_16x16x32_bf16 v[126:129], v[134:137], v[180:183], v[126:129]
	v_mfma_f32_16x16x32_bf16 v[122:125], v[142:145], v[180:183], v[122:125]
	v_mfma_f32_16x16x32_bf16 v[110:113], v[134:137], v[188:191], v[110:113]
	v_mfma_f32_16x16x32_bf16 v[106:109], v[142:145], v[188:191], v[106:109]
	v_mfma_f32_16x16x32_bf16 v[94:97], v[134:137], v[196:199], v[94:97]
	v_mfma_f32_16x16x32_bf16 v[90:93], v[142:145], v[196:199], v[90:93]
	v_mfma_f32_16x16x32_bf16 v[78:81], v[134:137], v[204:207], v[78:81]
	v_mfma_f32_16x16x32_bf16 v[74:77], v[142:145], v[204:207], v[74:77]
	s_setprio 0
	s_setprio 1
	v_mfma_f32_16x16x32_bf16 v[118:121], v[158:161], v[176:179], v[118:121]
	v_mfma_f32_16x16x32_bf16 v[114:117], v[166:169], v[176:179], v[114:117]
	v_mfma_f32_16x16x32_bf16 v[102:105], v[158:161], v[184:187], v[102:105]
	v_mfma_f32_16x16x32_bf16 v[98:101], v[166:169], v[184:187], v[98:101]
	v_mfma_f32_16x16x32_bf16 v[86:89], v[158:161], v[192:195], v[86:89]
	v_mfma_f32_16x16x32_bf16 v[82:85], v[166:169], v[192:195], v[82:85]
	v_mfma_f32_16x16x32_bf16 v[70:73], v[158:161], v[200:203], v[70:73]
	v_mfma_f32_16x16x32_bf16 v[66:69], v[166:169], v[200:203], v[66:69]
	v_mfma_f32_16x16x32_bf16 v[118:121], v[162:165], v[180:183], v[118:121]
	v_mfma_f32_16x16x32_bf16 v[114:117], v[170:173], v[180:183], v[114:117]
	v_mfma_f32_16x16x32_bf16 v[102:105], v[162:165], v[188:191], v[102:105]
	v_mfma_f32_16x16x32_bf16 v[98:101], v[170:173], v[188:191], v[98:101]
	v_mfma_f32_16x16x32_bf16 v[86:89], v[162:165], v[196:199], v[86:89]
	v_mfma_f32_16x16x32_bf16 v[82:85], v[170:173], v[196:199], v[82:85]
	v_mfma_f32_16x16x32_bf16 v[70:73], v[162:165], v[204:207], v[70:73]
	v_mfma_f32_16x16x32_bf16 v[66:69], v[170:173], v[204:207], v[66:69]
	s_setprio 0
	s_barrier
; #define PG8_STAGE(bufoff, gbase, voff) do { _Pragma("unroll") for (int _i = 0; _i < 2; ++_i) \
;         __builtin_amdgcn_global_load_lds((const unsigned*)((const char*)(gbase) + (voff)[_i]), (PG8_LAS unsigned*)(lds + (bufoff) + ldsw + _i * 8192), 16, 0, 0); } while (0)
; #define PG8_LDA(dst, b, h) do { _Pragma("unroll") for (int m = 0; m < 4; ++m) _Pragma("unroll") for (int k = 0; k < 2; ++k) dst[m][k] = *(const PG8_LAS bf16x8*)(lds + PG8_SA(b, h) + aoff + m * 2048 + k * 1024); } while (0)
; #define PG8_MMA(ai, bj, At, Bt) do { __builtin_amdgcn_s_setprio(1); _Pragma("unroll") for (int m = 0; m < 4; ++m) _Pragma("unroll") for (int n = 0; n < 2; ++n) _Pragma("unroll") for (int k = 0; k < 2; ++k) \
;         acc[ai][bj][m][n] = __builtin_amdgcn_mfma_f32_16x16x32_bf16(Bt[n][k], At[m][k], acc[ai][bj][m][n], 0, 0, 0); __builtin_amdgcn_s_setprio(0); } while (0)
; #define PG8_WAIT_V(n) asm volatile("s_waitcnt vmcnt(" #n ")" ::: "memory")
; #define PG8_WAIT_L(n) asm volatile("s_waitcnt lgkmcnt(" #n ")" ::: "memory")
; #define PG8_BAR __builtin_amdgcn_s_barrier()
; #define PG8_SCHED __builtin_amdgcn_sched_barrier(0)
; template <class Epi, class Sched, bool ALIGN_EPI = false, bool SP2 = false>
; __device__ __forceinline__ void gemm_phase(PG8_LAS unsigned char* lds, const Gemm g, const Sched& S, const Epi& E, int wave0) {
;     ...
;             PG8_WAIT_V(8); PG8_WAIT_L(0); PG8_BAR; PG8_MMA(0, 0, At, B0); PG8_MMA(0, 1, At, B1); PG8_BAR; PG8_SCHED;
;             PG8_LDA(At, 1, 1); PG8_STAGE(PG8_SB(1, 0), b3, voffB); PG8_STAGE(PG8_SB(1, 1), b3 + hstep, voffB); PG8_STAGE(PG8_SA(1, 0), a3, voffA);
;             PG8_WAIT_V(8); PG8_WAIT_L(0); PG8_BAR; PG8_MMA(1, 0, At, B0); PG8_MMA(1, 1, At, B1); PG8_BAR; PG8_SCHED;
	s_add_i32 s42, s86, s61
	v_lshl_add_u64 v[208:209], v[208:209], 0, s[34:35]
	s_mov_b32 m0, s42
	ds_read_b128 v[176:179], v175 offset:49152
	ds_read_b128 v[180:183], v175 offset:50176
	ds_read_b128 v[184:187], v175 offset:51200
	ds_read_b128 v[188:191], v175 offset:52224
	ds_read_b128 v[192:195], v175 offset:53248
	ds_read_b128 v[196:199], v175 offset:54272
	ds_read_b128 v[200:203], v175 offset:55296
	ds_read_b128 v[204:207], v175 offset:56320
	global_load_lds_dwordx4 v[208:209], off
	s_add_i32 m0, s42, 0x2000
	s_add_u32 s4, s4, 0x40080
	v_lshl_add_u64 v[208:209], v[210:211], 0, s[34:35]
	s_addc_u32 s5, s5, 0
	s_add_i32 s42, s87, s61
	global_load_lds_dwordx4 v[208:209], off
	v_lshl_add_u64 v[208:209], s[4:5], 0, v[150:151]
	s_mov_b32 m0, s42
	s_nop 0
	global_load_lds_dwordx4 v[208:209], off
	v_lshl_add_u64 v[208:209], s[4:5], 0, v[146:147]
	s_add_i32 m0, s42, 0x2000
	s_nop 0
	global_load_lds_dwordx4 v[208:209], off
	v_lshl_add_u64 v[208:209], v[212:213], 0, s[34:35]
	s_mov_b32 m0, s74
	s_nop 0
	global_load_lds_dwordx4 v[208:209], off
	v_lshl_add_u64 v[208:209], v[214:215], 0, s[34:35]
	s_mov_b32 m0, s75
	s_nop 0
	global_load_lds_dwordx4 v[208:209], off
	s_waitcnt vmcnt(8)
	s_waitcnt lgkmcnt(0)
	s_barrier
	s_setprio 1
	s_waitcnt lgkmcnt(0)
	v_mfma_f32_16x16x32_bf16 v[62:65], v[130:133], v[176:179], v[62:65]
	v_mfma_f32_16x16x32_bf16 v[58:61], v[138:141], v[176:179], v[58:61]
	v_mfma_f32_16x16x32_bf16 v[46:49], v[130:133], v[184:187], v[46:49]
	v_mfma_f32_16x16x32_bf16 v[42:45], v[138:141], v[184:187], v[42:45]
	v_mfma_f32_16x16x32_bf16 v[30:33], v[130:133], v[192:195], v[30:33]
	v_mfma_f32_16x16x32_bf16 v[26:29], v[138:141], v[192:195], v[26:29]
	v_mfma_f32_16x16x32_bf16 v[14:17], v[130:133], v[200:203], v[14:17]
	v_mfma_f32_16x16x32_bf16 v[10:13], v[138:141], v[200:203], v[10:13]
	v_mfma_f32_16x16x32_bf16 v[62:65], v[134:137], v[180:183], v[62:65]
	v_mfma_f32_16x16x32_bf16 v[58:61], v[142:145], v[180:183], v[58:61]
	v_mfma_f32_16x16x32_bf16 v[46:49], v[134:137], v[188:191], v[46:49]
	v_mfma_f32_16x16x32_bf16 v[42:45], v[142:145], v[188:191], v[42:45]
	v_mfma_f32_16x16x32_bf16 v[30:33], v[134:137], v[196:199], v[30:33]
	v_mfma_f32_16x16x32_bf16 v[26:29], v[142:145], v[196:199], v[26:29]
	v_mfma_f32_16x16x32_bf16 v[14:17], v[134:137], v[204:207], v[14:17]
	v_mfma_f32_16x16x32_bf16 v[10:13], v[142:145], v[204:207], v[10:13]
	s_setprio 0
	s_setprio 1
	v_mfma_f32_16x16x32_bf16 v[54:57], v[158:161], v[176:179], v[54:57]
	v_mfma_f32_16x16x32_bf16 v[50:53], v[166:169], v[176:179], v[50:53]
	v_mfma_f32_16x16x32_bf16 v[38:41], v[158:161], v[184:187], v[38:41]
	v_mfma_f32_16x16x32_bf16 v[34:37], v[166:169], v[184:187], v[34:37]
	v_mfma_f32_16x16x32_bf16 v[22:25], v[158:161], v[192:195], v[22:25]
	v_mfma_f32_16x16x32_bf16 v[18:21], v[166:169], v[192:195], v[18:21]
	v_mfma_f32_16x16x32_bf16 v[6:9], v[158:161], v[200:203], v[6:9]
	v_mfma_f32_16x16x32_bf16 v[2:5], v[166:169], v[200:203], v[2:5]
	v_mfma_f32_16x16x32_bf16 v[54:57], v[162:165], v[180:183], v[54:57]
	v_mfma_f32_16x16x32_bf16 v[50:53], v[170:173], v[180:183], v[50:53]
	v_mfma_f32_16x16x32_bf16 v[38:41], v[162:165], v[188:191], v[38:41]
	v_mfma_f32_16x16x32_bf16 v[34:37], v[170:173], v[188:191], v[34:37]
	v_mfma_f32_16x16x32_bf16 v[22:25], v[162:165], v[196:199], v[22:25]
	v_mfma_f32_16x16x32_bf16 v[18:21], v[170:173], v[196:199], v[18:21]
	v_mfma_f32_16x16x32_bf16 v[6:9], v[162:165], v[204:207], v[6:9]
	v_mfma_f32_16x16x32_bf16 v[2:5], v[170:173], v[204:207], v[2:5]
	s_setprio 0
	s_add_i32 s85, s85, 2
	s_add_u32 s0, s0, 0x100
	s_addc_u32 s1, s1, 0
	s_add_u32 s83, s83, 0x100
	s_addc_u32 s84, s84, 0
	s_cmp_gt_u32 s85, 13
	s_barrier
	s_cbranch_scc0 .LBB0_195
	s_and_b64 vcc, exec, s[48:49]
	s_cbranch_vccz .LBB0_198
	s_barrier

; #define PG8_STAGE(bufoff, gbase, voff) do { _Pragma("unroll") for (int _i = 0; _i < 2; ++_i) \
;         __builtin_amdgcn_global_load_lds((const unsigned*)((const char*)(gbase) + (voff)[_i]), (PG8_LAS unsigned*)(lds + (bufoff) + ldsw + _i * 8192), 16, 0, 0); } while (0)
; #define PG8_LDA(dst, b, h) do { _Pragma("unroll") for (int m = 0; m < 4; ++m) _Pragma("unroll") for (int k = 0; k < 2; ++k) dst[m][k] = *(const PG8_LAS bf16x8*)(lds + PG8_SA(b, h) + aoff + m * 2048 + k * 1024); } while (0)
; #define PG8_LDB(dst, b, h) do { _Pragma("unroll") for (int n = 0; n < 2; ++n) _Pragma("unroll") for (int k = 0; k < 2; ++k) dst[n][k] = *(const PG8_LAS bf16x8*)(lds + PG8_SB(b, h) + boff + n * 2048 + k * 1024); } while (0)
; #define PG8_MMA(ai, bj, At, Bt) do { __builtin_amdgcn_s_setprio(1); _Pragma("unroll") for (int m = 0; m < 4; ++m) _Pragma("unroll") for (int n = 0; n < 2; ++n) _Pragma("unroll") for (int k = 0; k < 2; ++k) \
;         acc[ai][bj][m][n] = __builtin_amdgcn_mfma_f32_16x16x32_bf16(Bt[n][k], At[m][k], acc[ai][bj][m][n], 0, 0, 0); __builtin_amdgcn_s_setprio(0); } while (0)
; #define PG8_WAIT_V(n) asm volatile("s_waitcnt vmcnt(" #n ")" ::: "memory")
; #define PG8_WAIT_L(n) asm volatile("s_waitcnt lgkmcnt(" #n ")" ::: "memory")
; #define PG8_BAR __builtin_amdgcn_s_barrier()
; #define PG8_SCHED __builtin_amdgcn_sched_barrier(0)
; template <class Epi, class Sched, bool ALIGN_EPI = false, bool SP2 = false>
; __device__ __forceinline__ void gemm_phase(PG8_LAS unsigned char* lds, const Gemm g, const Sched& S, const Epi& E, int wave0) {
;     ...
;             PG8_LDB(B0, 0, 0); PG8_LDB(B1, 0, 1); PG8_SCHED; PG8_LDA(At, 0, 0); PG8_STAGE(PG8_SA(1, 1), a1 + hstep, voffA);
;             PG8_WAIT_V(8); PG8_WAIT_L(0); PG8_BAR; PG8_MMA(0, 0, At, B0); PG8_MMA(0, 1, At, B1); PG8_BAR; PG8_SCHED;
;             PG8_LDA(At, 0, 1); PG8_STAGE(PG8_SB(0, 0), b2, voffB); PG8_STAGE(PG8_SB(0, 1), b2 + hstep, voffB); PG8_STAGE(PG8_SA(0, 0), a2, voffA);
;             PG8_WAIT_V(8); PG8_WAIT_L(0); PG8_BAR; PG8_MMA(1, 0, At, B0); PG8_MMA(1, 1, At, B1); PG8_BAR; PG8_SCHED;
.LBB0_812:
	s_add_i32 s36, 0, 0x10000
	v_add_u32_e32 v0, s36, v238
	ds_read_b128 v[36:39], v0
	ds_read_b128 v[48:51], v0 offset:1024
	ds_read_b128 v[68:71], v0 offset:2048
	ds_read_b128 v[80:83], v0 offset:3072
	s_add_u32 s4, s0, 0xfffe0080
	s_addc_u32 s5, s1, -1
	s_cmp_eq_u32 s66, 4
	s_cselect_b32 s47, s25, s5
	s_cselect_b32 s46, s63, s4
	s_cselect_b32 s5, s23, s65
	s_cselect_b32 s4, s31, s64
	s_add_i32 s67, 0, 0x14000
	v_add_u32_e32 v0, s67, v238
	ds_read_b128 v[100:103], v0
	ds_read_b128 v[104:107], v0 offset:1024
	ds_read_b128 v[124:127], v0 offset:2048
	ds_read_b128 v[128:131], v0 offset:3072
	v_lshl_add_u64 v[2:3], s[0:1], 0, v[204:205]
	s_add_i32 m0, s49, 0xc000
	ds_read_b128 v[156:159], v239
	ds_read_b128 v[160:163], v239 offset:1024
	ds_read_b128 v[172:175], v239 offset:2048
	ds_read_b128 v[176:179], v239 offset:3072
	ds_read_b128 v[180:183], v239 offset:4096
	ds_read_b128 v[184:187], v239 offset:5120
	ds_read_b128 v[188:191], v239 offset:6144
	ds_read_b128 v[192:195], v239 offset:7168
	global_load_lds_dwordx4 v[2:3], off
	v_lshl_add_u64 v[2:3], s[0:1], 0, v[206:207]
	s_add_i32 m0, s49, 0xe000
	s_nop 0
	global_load_lds_dwordx4 v[2:3], off
	s_waitcnt vmcnt(8)
	s_waitcnt lgkmcnt(0)
	s_barrier
	s_setprio 1
	s_waitcnt lgkmcnt(0)
	v_mfma_f32_16x16x32_bf16 v[56:59], v[36:39], v[156:159], v[56:59]
	v_mfma_f32_16x16x32_bf16 v[52:55], v[68:71], v[156:159], v[52:55]
	v_mfma_f32_16x16x32_bf16 v[88:91], v[36:39], v[172:175], v[88:91]
	v_mfma_f32_16x16x32_bf16 v[84:87], v[68:71], v[172:175], v[84:87]
	v_mfma_f32_16x16x32_bf16 v[112:115], v[36:39], v[180:183], v[112:115]
	v_mfma_f32_16x16x32_bf16 v[108:111], v[68:71], v[180:183], v[108:111]
	v_mfma_f32_16x16x32_bf16 v[136:139], v[36:39], v[188:191], v[136:139]
	v_mfma_f32_16x16x32_bf16 v[132:135], v[68:71], v[188:191], v[132:135]
	v_mfma_f32_16x16x32_bf16 v[56:59], v[48:51], v[160:163], v[56:59]
	v_mfma_f32_16x16x32_bf16 v[52:55], v[80:83], v[160:163], v[52:55]
	v_mfma_f32_16x16x32_bf16 v[88:91], v[48:51], v[176:179], v[88:91]
	v_mfma_f32_16x16x32_bf16 v[84:87], v[80:83], v[176:179], v[84:87]
	v_mfma_f32_16x16x32_bf16 v[112:115], v[48:51], v[184:187], v[112:115]
	v_mfma_f32_16x16x32_bf16 v[108:111], v[80:83], v[184:187], v[108:111]
	v_mfma_f32_16x16x32_bf16 v[136:139], v[48:51], v[192:195], v[136:139]
	v_mfma_f32_16x16x32_bf16 v[132:135], v[80:83], v[192:195], v[132:135]
	s_setprio 0
	s_setprio 1
	v_mfma_f32_16x16x32_bf16 v[168:171], v[100:103], v[156:159], v[168:171]
	v_mfma_f32_16x16x32_bf16 v[152:155], v[100:103], v[172:175], v[152:155]
	v_mfma_f32_16x16x32_bf16 v[148:151], v[124:127], v[172:175], v[148:151]
	v_mfma_f32_16x16x32_bf16 v[144:147], v[100:103], v[180:183], v[144:147]
	v_mfma_f32_16x16x32_bf16 v[140:143], v[124:127], v[180:183], v[140:143]
	v_mfma_f32_16x16x32_bf16 v[120:123], v[100:103], v[188:191], v[120:123]
	v_mfma_f32_16x16x32_bf16 v[116:119], v[124:127], v[188:191], v[116:119]
	v_mfma_f32_16x16x32_bf16 v[168:171], v[104:107], v[160:163], v[168:171]
	v_mfma_f32_16x16x32_bf16 v[156:159], v[124:127], v[156:159], v[164:167]
	v_mfma_f32_16x16x32_bf16 v[152:155], v[104:107], v[176:179], v[152:155]
	v_mfma_f32_16x16x32_bf16 v[148:151], v[128:131], v[176:179], v[148:151]
	v_mfma_f32_16x16x32_bf16 v[144:147], v[104:107], v[184:187], v[144:147]
	v_mfma_f32_16x16x32_bf16 v[140:143], v[128:131], v[184:187], v[140:143]
	v_mfma_f32_16x16x32_bf16 v[120:123], v[104:107], v[192:195], v[120:123]
	v_mfma_f32_16x16x32_bf16 v[116:119], v[128:131], v[192:195], v[116:119]
	v_mfma_f32_16x16x32_bf16 v[156:159], v[128:131], v[160:163], v[156:159]
	s_setprio 0
	s_barrier
	s_add_i32 s36, s36, s48
	v_lshl_add_u64 v[208:209], s[4:5], 0, v[200:201]
	s_mov_b32 m0, s36
	ds_read_b128 v[160:163], v239 offset:16384
	ds_read_b128 v[164:167], v239 offset:17408
	ds_read_b128 v[172:175], v239 offset:18432
	ds_read_b128 v[176:179], v239 offset:19456
	ds_read_b128 v[180:183], v239 offset:20480
	ds_read_b128 v[184:187], v239 offset:21504
	ds_read_b128 v[188:191], v239 offset:22528
	ds_read_b128 v[192:195], v239 offset:23552
	global_load_lds_dwordx4 v[208:209], off
	s_add_i32 m0, s36, 0x2000
	s_add_u32 s68, s4, 0x20000
	v_lshl_add_u64 v[210:211], s[4:5], 0, v[196:197]
	s_addc_u32 s69, s5, 0
	s_add_i32 s36, s67, s48
	global_load_lds_dwordx4 v[210:211], off
	v_lshl_add_u64 v[2:3], s[68:69], 0, v[200:201]
	s_mov_b32 m0, s36
	v_lshl_add_u64 v[212:213], s[46:47], 0, v[202:203]
	global_load_lds_dwordx4 v[2:3], off
	v_lshl_add_u64 v[2:3], s[68:69], 0, v[196:197]
	s_add_i32 m0, s36, 0x2000
	v_lshl_add_u64 v[214:215], s[46:47], 0, v[198:199]
	global_load_lds_dwordx4 v[2:3], off
	s_mov_b32 m0, s49
	s_nop 0
	global_load_lds_dwordx4 v[212:213], off
	s_mov_b32 m0, s50
	s_nop 0
	global_load_lds_dwordx4 v[214:215], off
	s_waitcnt vmcnt(8)
	s_waitcnt lgkmcnt(0)
	s_barrier
; #define PG8_STAGE(bufoff, gbase, voff) do { _Pragma("unroll") for (int _i = 0; _i < 2; ++_i) \
;         __builtin_amdgcn_global_load_lds((const unsigned*)((const char*)(gbase) + (voff)[_i]), (PG8_LAS unsigned*)(lds + (bufoff) + ldsw + _i * 8192), 16, 0, 0); } while (0)
; #define PG8_LDA(dst, b, h) do { _Pragma("unroll") for (int m = 0; m < 4; ++m) _Pragma("unroll") for (int k = 0; k < 2; ++k) dst[m][k] = *(const PG8_LAS bf16x8*)(lds + PG8_SA(b, h) + aoff + m * 2048 + k * 1024); } while (0)
; #define PG8_LDB(dst, b, h) do { _Pragma("unroll") for (int n = 0; n < 2; ++n) _Pragma("unroll") for (int k = 0; k < 2; ++k) dst[n][k] = *(const PG8_LAS bf16x8*)(lds + PG8_SB(b, h) + boff + n * 2048 + k * 1024); } while (0)
; #define PG8_MMA(ai, bj, At, Bt) do { __builtin_amdgcn_s_setprio(1); _Pragma("unroll") for (int m = 0; m < 4; ++m) _Pragma("unroll") for (int n = 0; n < 2; ++n) _Pragma("unroll") for (int k = 0; k < 2; ++k) \
;         acc[ai][bj][m][n] = __builtin_amdgcn_mfma_f32_16x16x32_bf16(Bt[n][k], At[m][k], acc[ai][bj][m][n], 0, 0, 0); __builtin_amdgcn_s_setprio(0); } while (0)
; #define PG8_WAIT_V(n) asm volatile("s_waitcnt vmcnt(" #n ")" ::: "memory")
; #define PG8_WAIT_L(n) asm volatile("s_waitcnt lgkmcnt(" #n ")" ::: "memory")
; #define PG8_BAR __builtin_amdgcn_s_barrier()
; #define PG8_SCHED __builtin_amdgcn_sched_barrier(0)
; template <class Epi, class Sched, bool ALIGN_EPI = false, bool SP2 = false>
; __device__ __forceinline__ void gemm_phase(PG8_LAS unsigned char* lds, const Gemm g, const Sched& S, const Epi& E, int wave0) {
;     ...
;             PG8_WAIT_V(8); PG8_WAIT_L(0); PG8_BAR; PG8_MMA(1, 0, At, B0); PG8_MMA(1, 1, At, B1); PG8_BAR; PG8_SCHED;
;             PG8_LDB(B0, 1, 0); PG8_LDB(B1, 1, 1); PG8_SCHED; PG8_LDA(At, 1, 0); PG8_STAGE(PG8_SA(0, 1), a2 + hstep, voffA);
;             PG8_WAIT_V(8); PG8_WAIT_L(0); PG8_BAR; PG8_MMA(0, 0, At, B0); PG8_MMA(0, 1, At, B1); PG8_BAR; PG8_SCHED;
	s_setprio 1
	s_waitcnt lgkmcnt(0)
	v_mfma_f32_16x16x32_bf16 v[96:99], v[36:39], v[160:163], v[96:99]
	v_mfma_f32_16x16x32_bf16 v[92:95], v[68:71], v[160:163], v[92:95]
	v_mfma_f32_16x16x32_bf16 v[64:67], v[36:39], v[172:175], v[64:67]
	v_mfma_f32_16x16x32_bf16 v[60:63], v[68:71], v[172:175], v[60:63]
	v_mfma_f32_16x16x32_bf16 v[32:35], v[36:39], v[180:183], v[32:35]
	v_mfma_f32_16x16x32_bf16 v[28:31], v[68:71], v[180:183], v[28:31]
	v_mfma_f32_16x16x32_bf16 v[16:19], v[36:39], v[188:191], v[16:19]
	v_mfma_f32_16x16x32_bf16 v[12:15], v[68:71], v[188:191], v[12:15]
	v_mfma_f32_16x16x32_bf16 v[96:99], v[48:51], v[164:167], v[96:99]
	v_mfma_f32_16x16x32_bf16 v[92:95], v[80:83], v[164:167], v[92:95]
	v_mfma_f32_16x16x32_bf16 v[64:67], v[48:51], v[176:179], v[64:67]
	v_mfma_f32_16x16x32_bf16 v[60:63], v[80:83], v[176:179], v[60:63]
	v_mfma_f32_16x16x32_bf16 v[32:35], v[48:51], v[184:187], v[32:35]
	v_mfma_f32_16x16x32_bf16 v[28:31], v[80:83], v[184:187], v[28:31]
	v_mfma_f32_16x16x32_bf16 v[16:19], v[48:51], v[192:195], v[16:19]
	v_mfma_f32_16x16x32_bf16 v[12:15], v[80:83], v[192:195], v[12:15]
	s_setprio 0
	s_setprio 1
	v_mfma_f32_16x16x32_bf16 v[44:47], v[100:103], v[172:175], v[44:47]
	v_mfma_f32_16x16x32_bf16 v[40:43], v[124:127], v[172:175], v[40:43]
	v_mfma_f32_16x16x32_bf16 v[24:27], v[100:103], v[180:183], v[24:27]
	v_mfma_f32_16x16x32_bf16 v[20:23], v[124:127], v[180:183], v[20:23]
	v_mfma_f32_16x16x32_bf16 v[8:11], v[100:103], v[188:191], v[8:11]
	v_mfma_f32_16x16x32_bf16 v[2:5], v[124:127], v[188:191], v[4:7]
	v_mfma_f32_16x16x32_bf16 v[36:39], v[100:103], v[160:163], v[76:79]
	v_mfma_f32_16x16x32_bf16 v[48:51], v[124:127], v[160:163], v[72:75]
	v_mfma_f32_16x16x32_bf16 v[44:47], v[104:107], v[176:179], v[44:47]
	v_mfma_f32_16x16x32_bf16 v[40:43], v[128:131], v[176:179], v[40:43]
	v_mfma_f32_16x16x32_bf16 v[24:27], v[104:107], v[184:187], v[24:27]
	v_mfma_f32_16x16x32_bf16 v[20:23], v[128:131], v[184:187], v[20:23]
	v_mfma_f32_16x16x32_bf16 v[8:11], v[104:107], v[192:195], v[8:11]
	v_mfma_f32_16x16x32_bf16 v[2:5], v[128:131], v[192:195], v[2:5]
	v_mfma_f32_16x16x32_bf16 v[36:39], v[104:107], v[164:167], v[36:39]
	v_mfma_f32_16x16x32_bf16 v[48:51], v[128:131], v[164:167], v[48:51]
	s_setprio 0
	s_barrier
	s_add_i32 s36, 0, 0x18000
	v_add_u32_e32 v0, s36, v238
	s_add_i32 s67, 0, 0x1c000
	ds_read_b128 v[68:71], v0
	ds_read_b128 v[72:75], v0 offset:1024
	ds_read_b128 v[76:79], v0 offset:2048
	ds_read_b128 v[80:83], v0 offset:3072
	v_add_u32_e32 v0, s67, v238
	ds_read_b128 v[100:103], v0
	ds_read_b128 v[104:107], v0 offset:1024
	ds_read_b128 v[124:127], v0 offset:2048
	ds_read_b128 v[128:131], v0 offset:3072
	s_add_u32 s46, s46, 0x20000
	s_addc_u32 s47, s47, 0
	s_mov_b32 m0, s51
	v_lshl_add_u64 v[6:7], s[46:47], 0, v[202:203]
	ds_read_b128 v[160:163], v239 offset:32768
	ds_read_b128 v[164:167], v239 offset:33792
	ds_read_b128 v[172:175], v239 offset:34816
	ds_read_b128 v[176:179], v239 offset:35840
	ds_read_b128 v[180:183], v239 offset:36864
	ds_read_b128 v[184:187], v239 offset:37888
	ds_read_b128 v[188:191], v239 offset:38912
	ds_read_b128 v[192:195], v239 offset:39936
	global_load_lds_dwordx4 v[6:7], off
	v_lshl_add_u64 v[6:7], s[46:47], 0, v[198:199]
	s_mov_b32 m0, s52
	s_nop 0
	global_load_lds_dwordx4 v[6:7], off
	s_waitcnt vmcnt(8)
	s_waitcnt lgkmcnt(0)
	s_barrier
	s_setprio 1
	s_waitcnt lgkmcnt(0)
	v_mfma_f32_16x16x32_bf16 v[56:59], v[68:71], v[160:163], v[56:59]
	v_mfma_f32_16x16x32_bf16 v[52:55], v[76:79], v[160:163], v[52:55]
	v_mfma_f32_16x16x32_bf16 v[88:91], v[68:71], v[172:175], v[88:91]
	v_mfma_f32_16x16x32_bf16 v[84:87], v[76:79], v[172:175], v[84:87]
	v_mfma_f32_16x16x32_bf16 v[112:115], v[68:71], v[180:183], v[112:115]
	v_mfma_f32_16x16x32_bf16 v[108:111], v[76:79], v[180:183], v[108:111]
	v_mfma_f32_16x16x32_bf16 v[136:139], v[68:71], v[188:191], v[136:139]
	v_mfma_f32_16x16x32_bf16 v[132:135], v[76:79], v[188:191], v[132:135]
	v_mfma_f32_16x16x32_bf16 v[56:59], v[72:75], v[164:167], v[56:59]
	v_mfma_f32_16x16x32_bf16 v[52:55], v[80:83], v[164:167], v[52:55]
	v_mfma_f32_16x16x32_bf16 v[88:91], v[72:75], v[176:179], v[88:91]
	v_mfma_f32_16x16x32_bf16 v[84:87], v[80:83], v[176:179], v[84:87]
	v_mfma_f32_16x16x32_bf16 v[112:115], v[72:75], v[184:187], v[112:115]
	v_mfma_f32_16x16x32_bf16 v[108:111], v[80:83], v[184:187], v[108:111]
	v_mfma_f32_16x16x32_bf16 v[136:139], v[72:75], v[192:195], v[136:139]
	v_mfma_f32_16x16x32_bf16 v[132:135], v[80:83], v[192:195], v[132:135]
	s_setprio 0
	s_setprio 1
	v_mfma_f32_16x16x32_bf16 v[168:171], v[100:103], v[160:163], v[168:171]
	v_mfma_f32_16x16x32_bf16 v[156:159], v[124:127], v[160:163], v[156:159]
	v_mfma_f32_16x16x32_bf16 v[152:155], v[100:103], v[172:175], v[152:155]
	v_mfma_f32_16x16x32_bf16 v[148:151], v[124:127], v[172:175], v[148:151]
	v_mfma_f32_16x16x32_bf16 v[144:147], v[100:103], v[180:183], v[144:147]
	v_mfma_f32_16x16x32_bf16 v[140:143], v[124:127], v[180:183], v[140:143]
	v_mfma_f32_16x16x32_bf16 v[120:123], v[100:103], v[188:191], v[120:123]
	v_mfma_f32_16x16x32_bf16 v[116:119], v[124:127], v[188:191], v[116:119]
	v_mfma_f32_16x16x32_bf16 v[168:171], v[104:107], v[164:167], v[168:171]
	v_mfma_f32_16x16x32_bf16 v[164:167], v[128:131], v[164:167], v[156:159]
	v_mfma_f32_16x16x32_bf16 v[152:155], v[104:107], v[176:179], v[152:155]
	v_mfma_f32_16x16x32_bf16 v[148:151], v[128:131], v[176:179], v[148:151]
	v_mfma_f32_16x16x32_bf16 v[144:147], v[104:107], v[184:187], v[144:147]
	v_mfma_f32_16x16x32_bf16 v[140:143], v[128:131], v[184:187], v[140:143]
	v_mfma_f32_16x16x32_bf16 v[120:123], v[104:107], v[192:195], v[120:123]
	v_mfma_f32_16x16x32_bf16 v[116:119], v[128:131], v[192:195], v[116:119]
	s_setprio 0
	s_barrier
; #define PG8_STAGE(bufoff, gbase, voff) do { _Pragma("unroll") for (int _i = 0; _i < 2; ++_i) \
;         __builtin_amdgcn_global_load_lds((const unsigned*)((const char*)(gbase) + (voff)[_i]), (PG8_LAS unsigned*)(lds + (bufoff) + ldsw + _i * 8192), 16, 0, 0); } while (0)
; #define PG8_LDA(dst, b, h) do { _Pragma("unroll") for (int m = 0; m < 4; ++m) _Pragma("unroll") for (int k = 0; k < 2; ++k) dst[m][k] = *(const PG8_LAS bf16x8*)(lds + PG8_SA(b, h) + aoff + m * 2048 + k * 1024); } while (0)
; #define PG8_MMA(ai, bj, At, Bt) do { __builtin_amdgcn_s_setprio(1); _Pragma("unroll") for (int m = 0; m < 4; ++m) _Pragma("unroll") for (int n = 0; n < 2; ++n) _Pragma("unroll") for (int k = 0; k < 2; ++k) \
;         acc[ai][bj][m][n] = __builtin_amdgcn_mfma_f32_16x16x32_bf16(Bt[n][k], At[m][k], acc[ai][bj][m][n], 0, 0, 0); __builtin_amdgcn_s_setprio(0); } while (0)
; #define PG8_WAIT_V(n) asm volatile("s_waitcnt vmcnt(" #n ")" ::: "memory")
; #define PG8_WAIT_L(n) asm volatile("s_waitcnt lgkmcnt(" #n ")" ::: "memory")
; #define PG8_BAR __builtin_amdgcn_s_barrier()
; #define PG8_SCHED __builtin_amdgcn_sched_barrier(0)
; template <class Epi, class Sched, bool ALIGN_EPI = false, bool SP2 = false>
; __device__ __forceinline__ void gemm_phase(PG8_LAS unsigned char* lds, const Gemm g, const Sched& S, const Epi& E, int wave0) {
;     ...
;             PG8_WAIT_V(8); PG8_WAIT_L(0); PG8_BAR; PG8_MMA(0, 0, At, B0); PG8_MMA(0, 1, At, B1); PG8_BAR; PG8_SCHED;
;             PG8_LDA(At, 1, 1); PG8_STAGE(PG8_SB(1, 0), b3, voffB); PG8_STAGE(PG8_SB(1, 1), b3 + hstep, voffB); PG8_STAGE(PG8_SA(1, 0), a3, voffA);
;             PG8_WAIT_V(8); PG8_WAIT_L(0); PG8_BAR; PG8_MMA(1, 0, At, B0); PG8_MMA(1, 1, At, B1); PG8_BAR; PG8_SCHED;
	s_add_i32 s36, s36, s48
	v_lshl_add_u64 v[6:7], v[208:209], 0, s[34:35]
	s_mov_b32 m0, s36
	ds_read_b128 v[156:159], v239 offset:49152
	ds_read_b128 v[160:163], v239 offset:50176
	ds_read_b128 v[172:175], v239 offset:51200
	ds_read_b128 v[176:179], v239 offset:52224
	ds_read_b128 v[180:183], v239 offset:53248
	ds_read_b128 v[184:187], v239 offset:54272
	ds_read_b128 v[188:191], v239 offset:55296
	ds_read_b128 v[192:195], v239 offset:56320
	global_load_lds_dwordx4 v[6:7], off
	s_add_i32 m0, s36, 0x2000
	s_add_u32 s4, s4, 0x20080
	v_lshl_add_u64 v[6:7], v[210:211], 0, s[34:35]
	s_addc_u32 s5, s5, 0
	s_add_i32 s36, s67, s48
	global_load_lds_dwordx4 v[6:7], off
	v_lshl_add_u64 v[6:7], s[4:5], 0, v[200:201]
	s_mov_b32 m0, s36
	s_nop 0
	global_load_lds_dwordx4 v[6:7], off
	v_lshl_add_u64 v[6:7], s[4:5], 0, v[196:197]
	s_add_i32 m0, s36, 0x2000
	s_nop 0
	global_load_lds_dwordx4 v[6:7], off
	v_lshl_add_u64 v[6:7], v[212:213], 0, s[34:35]
	s_mov_b32 m0, s57
	s_nop 0
	global_load_lds_dwordx4 v[6:7], off
	v_lshl_add_u64 v[6:7], v[214:215], 0, s[34:35]
	s_mov_b32 m0, s58
	s_nop 0
	global_load_lds_dwordx4 v[6:7], off
	s_waitcnt vmcnt(8)
	s_waitcnt lgkmcnt(0)
	s_barrier
	s_setprio 1
	s_waitcnt lgkmcnt(0)
	v_mfma_f32_16x16x32_bf16 v[96:99], v[68:71], v[156:159], v[96:99]
	v_mfma_f32_16x16x32_bf16 v[92:95], v[76:79], v[156:159], v[92:95]
	v_mfma_f32_16x16x32_bf16 v[64:67], v[68:71], v[172:175], v[64:67]
	v_mfma_f32_16x16x32_bf16 v[60:63], v[76:79], v[172:175], v[60:63]
	v_mfma_f32_16x16x32_bf16 v[32:35], v[68:71], v[180:183], v[32:35]
	v_mfma_f32_16x16x32_bf16 v[28:31], v[76:79], v[180:183], v[28:31]
	v_mfma_f32_16x16x32_bf16 v[16:19], v[68:71], v[188:191], v[16:19]
	v_mfma_f32_16x16x32_bf16 v[12:15], v[76:79], v[188:191], v[12:15]
	v_mfma_f32_16x16x32_bf16 v[96:99], v[72:75], v[160:163], v[96:99]
	v_mfma_f32_16x16x32_bf16 v[92:95], v[80:83], v[160:163], v[92:95]
	v_mfma_f32_16x16x32_bf16 v[64:67], v[72:75], v[176:179], v[64:67]
	v_mfma_f32_16x16x32_bf16 v[60:63], v[80:83], v[176:179], v[60:63]
	v_mfma_f32_16x16x32_bf16 v[32:35], v[72:75], v[184:187], v[32:35]
	v_mfma_f32_16x16x32_bf16 v[28:31], v[80:83], v[184:187], v[28:31]
	v_mfma_f32_16x16x32_bf16 v[16:19], v[72:75], v[192:195], v[16:19]
	v_mfma_f32_16x16x32_bf16 v[12:15], v[80:83], v[192:195], v[12:15]
	s_setprio 0
	s_setprio 1
	v_mfma_f32_16x16x32_bf16 v[36:39], v[100:103], v[156:159], v[36:39]
	v_mfma_f32_16x16x32_bf16 v[76:79], v[104:107], v[160:163], v[36:39]
	v_mfma_f32_16x16x32_bf16 v[36:39], v[124:127], v[156:159], v[48:51]
	v_mfma_f32_16x16x32_bf16 v[72:75], v[128:131], v[160:163], v[36:39]
	v_mfma_f32_16x16x32_bf16 v[36:39], v[100:103], v[172:175], v[44:47]
	v_mfma_f32_16x16x32_bf16 v[44:47], v[104:107], v[176:179], v[36:39]
	v_mfma_f32_16x16x32_bf16 v[36:39], v[124:127], v[172:175], v[40:43]
	v_mfma_f32_16x16x32_bf16 v[24:27], v[100:103], v[180:183], v[24:27]
	v_mfma_f32_16x16x32_bf16 v[20:23], v[124:127], v[180:183], v[20:23]
	v_mfma_f32_16x16x32_bf16 v[6:9], v[100:103], v[188:191], v[8:11]
	v_mfma_f32_16x16x32_bf16 v[2:5], v[124:127], v[188:191], v[2:5]
	v_mfma_f32_16x16x32_bf16 v[40:43], v[128:131], v[176:179], v[36:39]
	v_mfma_f32_16x16x32_bf16 v[24:27], v[104:107], v[184:187], v[24:27]
	v_mfma_f32_16x16x32_bf16 v[20:23], v[128:131], v[184:187], v[20:23]
	v_mfma_f32_16x16x32_bf16 v[8:11], v[104:107], v[192:195], v[6:9]
	v_mfma_f32_16x16x32_bf16 v[4:7], v[128:131], v[192:195], v[2:5]
	s_setprio 0
	s_add_i32 s66, s66, 2
	s_add_u32 s0, s0, 0x100
	s_addc_u32 s1, s1, 0
	s_add_u32 s64, s64, 0x100
	s_addc_u32 s65, s65, 0
	s_cmp_gt_u32 s66, 5
	s_barrier
	s_cbranch_scc0 .LBB0_812
	s_and_b64 vcc, exec, s[20:21]
	s_cbranch_vccz .LBB0_815
	s_barrier

; #define PG8_STAGE(bufoff, gbase, voff) do { _Pragma("unroll") for (int _i = 0; _i < 2; ++_i) \
;         __builtin_amdgcn_global_load_lds((const unsigned*)((const char*)(gbase) + (voff)[_i]), (PG8_LAS unsigned*)(lds + (bufoff) + ldsw + _i * 8192), 16, 0, 0); } while (0)
; #define PG8_LDA(dst, b, h) do { _Pragma("unroll") for (int m = 0; m < 4; ++m) _Pragma("unroll") for (int k = 0; k < 2; ++k) dst[m][k] = *(const PG8_LAS bf16x8*)(lds + PG8_SA(b, h) + aoff + m * 2048 + k * 1024); } while (0)
; #define PG8_LDB(dst, b, h) do { _Pragma("unroll") for (int n = 0; n < 2; ++n) _Pragma("unroll") for (int k = 0; k < 2; ++k) dst[n][k] = *(const PG8_LAS bf16x8*)(lds + PG8_SB(b, h) + boff + n * 2048 + k * 1024); } while (0)
; #define PG8_MMA(ai, bj, At, Bt) do { __builtin_amdgcn_s_setprio(1); _Pragma("unroll") for (int m = 0; m < 4; ++m) _Pragma("unroll") for (int n = 0; n < 2; ++n) _Pragma("unroll") for (int k = 0; k < 2; ++k) \
;         acc[ai][bj][m][n] = __builtin_amdgcn_mfma_f32_16x16x32_bf16(Bt[n][k], At[m][k], acc[ai][bj][m][n], 0, 0, 0); __builtin_amdgcn_s_setprio(0); } while (0)
; #define PG8_WAIT_V(n) asm volatile("s_waitcnt vmcnt(" #n ")" ::: "memory")
; #define PG8_WAIT_L(n) asm volatile("s_waitcnt lgkmcnt(" #n ")" ::: "memory")
; #define PG8_BAR __builtin_amdgcn_s_barrier()
; #define PG8_SCHED __builtin_amdgcn_sched_barrier(0)
; template <class Epi, class Sched, bool ALIGN_EPI = false, bool SP2 = false>
; __device__ __forceinline__ void gemm_phase(PG8_LAS unsigned char* lds, const Gemm g, const Sched& S, const Epi& E, int wave0) {
;     ...
;             PG8_LDB(B0, 0, 0); PG8_LDB(B1, 0, 1); PG8_SCHED; PG8_LDA(At, 0, 0); PG8_STAGE(PG8_SA(1, 1), a1 + hstep, voffA);
;             PG8_WAIT_V(8); PG8_WAIT_L(0); PG8_BAR; PG8_MMA(0, 0, At, B0); PG8_MMA(0, 1, At, B1); PG8_BAR; PG8_SCHED;
;             PG8_LDA(At, 0, 1); PG8_STAGE(PG8_SB(0, 0), b2, voffB); PG8_STAGE(PG8_SB(0, 1), b2 + hstep, voffB); PG8_STAGE(PG8_SA(0, 0), a2, voffA);
;             PG8_WAIT_V(8); PG8_WAIT_L(0); PG8_BAR; PG8_MMA(1, 0, At, B0); PG8_MMA(1, 1, At, B1); PG8_BAR; PG8_SCHED;
.LBB0_997:
	s_add_i32 s36, 0, 0x10000
	s_add_i32 s70, 0, 0x14000
	v_add_u32_e32 v156, s36, v145
	v_add_u32_e32 v172, s70, v145
	ds_read_b128 v[140:143], v156
	ds_read_b128 v[148:151], v156 offset:1024
	ds_read_b128 v[152:155], v156 offset:2048
	ds_read_b128 v[156:159], v156 offset:3072
	s_add_u32 s28, s46, 0xfffc0080
	s_addc_u32 s29, s47, -1
	s_cmp_eq_u32 s67, 12
	s_cselect_b32 s49, s31, s29
	s_cselect_b32 s48, s63, s28
	s_cselect_b32 s29, s25, s66
	s_cselect_b32 s28, s64, s65
	ds_read_b128 v[160:163], v172
	ds_read_b128 v[164:167], v172 offset:1024
	ds_read_b128 v[168:171], v172 offset:2048
	ds_read_b128 v[172:175], v172 offset:3072
	v_lshl_add_u64 v[208:209], s[46:47], 0, v[136:137]
	s_add_i32 m0, s55, 0xc000
	ds_read_b128 v[176:179], v147
	ds_read_b128 v[180:183], v147 offset:1024
	ds_read_b128 v[184:187], v147 offset:2048
	ds_read_b128 v[188:191], v147 offset:3072
	ds_read_b128 v[192:195], v147 offset:4096
	ds_read_b128 v[196:199], v147 offset:5120
	ds_read_b128 v[200:203], v147 offset:6144
	ds_read_b128 v[204:207], v147 offset:7168
	global_load_lds_dwordx4 v[208:209], off
	v_lshl_add_u64 v[208:209], s[46:47], 0, v[138:139]
	s_add_i32 m0, s55, 0xe000
	s_nop 0
	global_load_lds_dwordx4 v[208:209], off
	s_waitcnt vmcnt(8)
	s_waitcnt lgkmcnt(0)
	s_barrier
	s_setprio 1
	s_waitcnt lgkmcnt(0)
	v_mfma_f32_16x16x32_bf16 v[126:129], v[140:143], v[176:179], v[126:129]
	v_mfma_f32_16x16x32_bf16 v[122:125], v[152:155], v[176:179], v[122:125]
	v_mfma_f32_16x16x32_bf16 v[110:113], v[140:143], v[184:187], v[110:113]
	v_mfma_f32_16x16x32_bf16 v[106:109], v[152:155], v[184:187], v[106:109]
	v_mfma_f32_16x16x32_bf16 v[94:97], v[140:143], v[192:195], v[94:97]
	v_mfma_f32_16x16x32_bf16 v[90:93], v[152:155], v[192:195], v[90:93]
	v_mfma_f32_16x16x32_bf16 v[78:81], v[140:143], v[200:203], v[78:81]
	v_mfma_f32_16x16x32_bf16 v[74:77], v[152:155], v[200:203], v[74:77]
	v_mfma_f32_16x16x32_bf16 v[126:129], v[148:151], v[180:183], v[126:129]
	v_mfma_f32_16x16x32_bf16 v[122:125], v[156:159], v[180:183], v[122:125]
	v_mfma_f32_16x16x32_bf16 v[110:113], v[148:151], v[188:191], v[110:113]
	v_mfma_f32_16x16x32_bf16 v[106:109], v[156:159], v[188:191], v[106:109]
	v_mfma_f32_16x16x32_bf16 v[94:97], v[148:151], v[196:199], v[94:97]
	v_mfma_f32_16x16x32_bf16 v[90:93], v[156:159], v[196:199], v[90:93]
	v_mfma_f32_16x16x32_bf16 v[78:81], v[148:151], v[204:207], v[78:81]
	v_mfma_f32_16x16x32_bf16 v[74:77], v[156:159], v[204:207], v[74:77]
	s_setprio 0
	s_setprio 1
	v_mfma_f32_16x16x32_bf16 v[118:121], v[160:163], v[176:179], v[118:121]
	v_mfma_f32_16x16x32_bf16 v[114:117], v[168:171], v[176:179], v[114:117]
	v_mfma_f32_16x16x32_bf16 v[102:105], v[160:163], v[184:187], v[102:105]
	v_mfma_f32_16x16x32_bf16 v[98:101], v[168:171], v[184:187], v[98:101]
	v_mfma_f32_16x16x32_bf16 v[86:89], v[160:163], v[192:195], v[86:89]
	v_mfma_f32_16x16x32_bf16 v[82:85], v[168:171], v[192:195], v[82:85]
	v_mfma_f32_16x16x32_bf16 v[70:73], v[160:163], v[200:203], v[70:73]
	v_mfma_f32_16x16x32_bf16 v[66:69], v[168:171], v[200:203], v[66:69]
	v_mfma_f32_16x16x32_bf16 v[118:121], v[164:167], v[180:183], v[118:121]
	v_mfma_f32_16x16x32_bf16 v[114:117], v[172:175], v[180:183], v[114:117]
	v_mfma_f32_16x16x32_bf16 v[102:105], v[164:167], v[188:191], v[102:105]
	v_mfma_f32_16x16x32_bf16 v[98:101], v[172:175], v[188:191], v[98:101]
	v_mfma_f32_16x16x32_bf16 v[86:89], v[164:167], v[196:199], v[86:89]
	v_mfma_f32_16x16x32_bf16 v[82:85], v[172:175], v[196:199], v[82:85]
	v_mfma_f32_16x16x32_bf16 v[70:73], v[164:167], v[204:207], v[70:73]
	v_mfma_f32_16x16x32_bf16 v[66:69], v[172:175], v[204:207], v[66:69]
	s_setprio 0
	s_barrier
	s_add_i32 s36, s36, s52
	v_lshl_add_u64 v[208:209], s[28:29], 0, v[0:1]
	s_mov_b32 m0, s36
	ds_read_b128 v[176:179], v147 offset:16384
	ds_read_b128 v[180:183], v147 offset:17408
	ds_read_b128 v[184:187], v147 offset:18432
	ds_read_b128 v[188:191], v147 offset:19456
	ds_read_b128 v[192:195], v147 offset:20480
	ds_read_b128 v[196:199], v147 offset:21504
	ds_read_b128 v[200:203], v147 offset:22528
	ds_read_b128 v[204:207], v147 offset:23552
	global_load_lds_dwordx4 v[208:209], off
	s_add_i32 m0, s36, 0x2000
	s_add_u32 s68, s28, 0x40000
	v_lshl_add_u64 v[210:211], s[28:29], 0, v[130:131]
	s_addc_u32 s69, s29, 0
	s_add_i32 s36, s70, s52
	global_load_lds_dwordx4 v[210:211], off
	v_lshl_add_u64 v[212:213], s[68:69], 0, v[0:1]
	s_mov_b32 m0, s36
	v_lshl_add_u64 v[214:215], s[48:49], 0, v[132:133]
	global_load_lds_dwordx4 v[212:213], off
	v_lshl_add_u64 v[212:213], s[68:69], 0, v[130:131]
	s_add_i32 m0, s36, 0x2000
	s_nop 0
	global_load_lds_dwordx4 v[212:213], off
	v_lshl_add_u64 v[212:213], s[48:49], 0, v[134:135]
	s_mov_b32 m0, s55
	s_nop 0
	global_load_lds_dwordx4 v[212:213], off
	s_mov_b32 m0, s56
	s_nop 0
	global_load_lds_dwordx4 v[214:215], off
	s_waitcnt vmcnt(8)
	s_waitcnt lgkmcnt(0)
	s_barrier
; #define PG8_STAGE(bufoff, gbase, voff) do { _Pragma("unroll") for (int _i = 0; _i < 2; ++_i) \
;         __builtin_amdgcn_global_load_lds((const unsigned*)((const char*)(gbase) + (voff)[_i]), (PG8_LAS unsigned*)(lds + (bufoff) + ldsw + _i * 8192), 16, 0, 0); } while (0)
; #define PG8_LDA(dst, b, h) do { _Pragma("unroll") for (int m = 0; m < 4; ++m) _Pragma("unroll") for (int k = 0; k < 2; ++k) dst[m][k] = *(const PG8_LAS bf16x8*)(lds + PG8_SA(b, h) + aoff + m * 2048 + k * 1024); } while (0)
; #define PG8_LDB(dst, b, h) do { _Pragma("unroll") for (int n = 0; n < 2; ++n) _Pragma("unroll") for (int k = 0; k < 2; ++k) dst[n][k] = *(const PG8_LAS bf16x8*)(lds + PG8_SB(b, h) + boff + n * 2048 + k * 1024); } while (0)
; #define PG8_MMA(ai, bj, At, Bt) do { __builtin_amdgcn_s_setprio(1); _Pragma("unroll") for (int m = 0; m < 4; ++m) _Pragma("unroll") for (int n = 0; n < 2; ++n) _Pragma("unroll") for (int k = 0; k < 2; ++k) \
;         acc[ai][bj][m][n] = __builtin_amdgcn_mfma_f32_16x16x32_bf16(Bt[n][k], At[m][k], acc[ai][bj][m][n], 0, 0, 0); __builtin_amdgcn_s_setprio(0); } while (0)
; #define PG8_WAIT_V(n) asm volatile("s_waitcnt vmcnt(" #n ")" ::: "memory")
; #define PG8_WAIT_L(n) asm volatile("s_waitcnt lgkmcnt(" #n ")" ::: "memory")
; #define PG8_BAR __builtin_amdgcn_s_barrier()
; #define PG8_SCHED __builtin_amdgcn_sched_barrier(0)
; template <class Epi, class Sched, bool ALIGN_EPI = false, bool SP2 = false>
; __device__ __forceinline__ void gemm_phase(PG8_LAS unsigned char* lds, const Gemm g, const Sched& S, const Epi& E, int wave0) {
;     ...
;             PG8_WAIT_V(8); PG8_WAIT_L(0); PG8_BAR; PG8_MMA(1, 0, At, B0); PG8_MMA(1, 1, At, B1); PG8_BAR; PG8_SCHED;
;             PG8_LDB(B0, 1, 0); PG8_LDB(B1, 1, 1); PG8_SCHED; PG8_LDA(At, 1, 0); PG8_STAGE(PG8_SA(0, 1), a2 + hstep, voffA);
;             PG8_WAIT_V(8); PG8_WAIT_L(0); PG8_BAR; PG8_MMA(0, 0, At, B0); PG8_MMA(0, 1, At, B1); PG8_BAR; PG8_SCHED;
	s_setprio 1
	s_waitcnt lgkmcnt(0)
	v_mfma_f32_16x16x32_bf16 v[58:61], v[140:143], v[176:179], v[58:61]
	v_mfma_f32_16x16x32_bf16 v[62:65], v[152:155], v[176:179], v[62:65]
	v_mfma_f32_16x16x32_bf16 v[42:45], v[140:143], v[184:187], v[42:45]
	v_mfma_f32_16x16x32_bf16 v[46:49], v[152:155], v[184:187], v[46:49]
	v_mfma_f32_16x16x32_bf16 v[26:29], v[140:143], v[192:195], v[26:29]
	v_mfma_f32_16x16x32_bf16 v[30:33], v[152:155], v[192:195], v[30:33]
	v_mfma_f32_16x16x32_bf16 v[10:13], v[140:143], v[200:203], v[10:13]
	v_mfma_f32_16x16x32_bf16 v[14:17], v[152:155], v[200:203], v[14:17]
	v_mfma_f32_16x16x32_bf16 v[58:61], v[148:151], v[180:183], v[58:61]
	v_mfma_f32_16x16x32_bf16 v[62:65], v[156:159], v[180:183], v[62:65]
	v_mfma_f32_16x16x32_bf16 v[42:45], v[148:151], v[188:191], v[42:45]
	v_mfma_f32_16x16x32_bf16 v[46:49], v[156:159], v[188:191], v[46:49]
	v_mfma_f32_16x16x32_bf16 v[26:29], v[148:151], v[196:199], v[26:29]
	v_mfma_f32_16x16x32_bf16 v[30:33], v[156:159], v[196:199], v[30:33]
	v_mfma_f32_16x16x32_bf16 v[10:13], v[148:151], v[204:207], v[10:13]
	v_mfma_f32_16x16x32_bf16 v[14:17], v[156:159], v[204:207], v[14:17]
	s_setprio 0
	s_setprio 1
	v_mfma_f32_16x16x32_bf16 v[54:57], v[160:163], v[176:179], v[54:57]
	v_mfma_f32_16x16x32_bf16 v[50:53], v[168:171], v[176:179], v[50:53]
	v_mfma_f32_16x16x32_bf16 v[38:41], v[160:163], v[184:187], v[38:41]
	v_mfma_f32_16x16x32_bf16 v[34:37], v[168:171], v[184:187], v[34:37]
	v_mfma_f32_16x16x32_bf16 v[22:25], v[160:163], v[192:195], v[22:25]
	v_mfma_f32_16x16x32_bf16 v[18:21], v[168:171], v[192:195], v[18:21]
	v_mfma_f32_16x16x32_bf16 v[6:9], v[160:163], v[200:203], v[6:9]
	v_mfma_f32_16x16x32_bf16 v[2:5], v[168:171], v[200:203], v[2:5]
	v_mfma_f32_16x16x32_bf16 v[54:57], v[164:167], v[180:183], v[54:57]
	v_mfma_f32_16x16x32_bf16 v[50:53], v[172:175], v[180:183], v[50:53]
	v_mfma_f32_16x16x32_bf16 v[38:41], v[164:167], v[188:191], v[38:41]
	v_mfma_f32_16x16x32_bf16 v[34:37], v[172:175], v[188:191], v[34:37]
	v_mfma_f32_16x16x32_bf16 v[22:25], v[164:167], v[196:199], v[22:25]
	v_mfma_f32_16x16x32_bf16 v[18:21], v[172:175], v[196:199], v[18:21]
	v_mfma_f32_16x16x32_bf16 v[6:9], v[164:167], v[204:207], v[6:9]
	v_mfma_f32_16x16x32_bf16 v[2:5], v[172:175], v[204:207], v[2:5]
	s_setprio 0
	s_barrier
	s_add_i32 s36, 0, 0x18000
	s_add_i32 s68, 0, 0x1c000
	v_add_u32_e32 v156, s36, v145
	v_add_u32_e32 v172, s68, v145
	ds_read_b128 v[140:143], v156
	ds_read_b128 v[148:151], v156 offset:1024
	ds_read_b128 v[152:155], v156 offset:2048
	ds_read_b128 v[156:159], v156 offset:3072
	ds_read_b128 v[160:163], v172
	ds_read_b128 v[164:167], v172 offset:1024
	ds_read_b128 v[168:171], v172 offset:2048
	ds_read_b128 v[172:175], v172 offset:3072
	s_add_u32 s48, s48, 0x40000
	s_addc_u32 s49, s49, 0
	s_mov_b32 m0, s57
	v_lshl_add_u64 v[216:217], s[48:49], 0, v[134:135]
	ds_read_b128 v[176:179], v147 offset:32768
	ds_read_b128 v[180:183], v147 offset:33792
	ds_read_b128 v[184:187], v147 offset:34816
	ds_read_b128 v[188:191], v147 offset:35840
	ds_read_b128 v[192:195], v147 offset:36864
	ds_read_b128 v[196:199], v147 offset:37888
	ds_read_b128 v[200:203], v147 offset:38912
	ds_read_b128 v[204:207], v147 offset:39936
	global_load_lds_dwordx4 v[216:217], off
	v_lshl_add_u64 v[216:217], s[48:49], 0, v[132:133]
	s_mov_b32 m0, s58
	s_nop 0
	global_load_lds_dwordx4 v[216:217], off
	s_waitcnt vmcnt(8)
	s_waitcnt lgkmcnt(0)
	s_barrier
	s_setprio 1
	s_waitcnt lgkmcnt(0)
	v_mfma_f32_16x16x32_bf16 v[126:129], v[140:143], v[176:179], v[126:129]
	v_mfma_f32_16x16x32_bf16 v[122:125], v[152:155], v[176:179], v[122:125]
	v_mfma_f32_16x16x32_bf16 v[110:113], v[140:143], v[184:187], v[110:113]
	v_mfma_f32_16x16x32_bf16 v[106:109], v[152:155], v[184:187], v[106:109]
	v_mfma_f32_16x16x32_bf16 v[94:97], v[140:143], v[192:195], v[94:97]
	v_mfma_f32_16x16x32_bf16 v[90:93], v[152:155], v[192:195], v[90:93]
	v_mfma_f32_16x16x32_bf16 v[78:81], v[140:143], v[200:203], v[78:81]
	v_mfma_f32_16x16x32_bf16 v[74:77], v[152:155], v[200:203], v[74:77]
	v_mfma_f32_16x16x32_bf16 v[126:129], v[148:151], v[180:183], v[126:129]
	v_mfma_f32_16x16x32_bf16 v[122:125], v[156:159], v[180:183], v[122:125]
	v_mfma_f32_16x16x32_bf16 v[110:113], v[148:151], v[188:191], v[110:113]
	v_mfma_f32_16x16x32_bf16 v[106:109], v[156:159], v[188:191], v[106:109]
	v_mfma_f32_16x16x32_bf16 v[94:97], v[148:151], v[196:199], v[94:97]
	v_mfma_f32_16x16x32_bf16 v[90:93], v[156:159], v[196:199], v[90:93]
	v_mfma_f32_16x16x32_bf16 v[78:81], v[148:151], v[204:207], v[78:81]
	v_mfma_f32_16x16x32_bf16 v[74:77], v[156:159], v[204:207], v[74:77]
	s_setprio 0
	s_setprio 1
	v_mfma_f32_16x16x32_bf16 v[118:121], v[160:163], v[176:179], v[118:121]
	v_mfma_f32_16x16x32_bf16 v[114:117], v[168:171], v[176:179], v[114:117]
	v_mfma_f32_16x16x32_bf16 v[102:105], v[160:163], v[184:187], v[102:105]
	v_mfma_f32_16x16x32_bf16 v[98:101], v[168:171], v[184:187], v[98:101]
	v_mfma_f32_16x16x32_bf16 v[86:89], v[160:163], v[192:195], v[86:89]
	v_mfma_f32_16x16x32_bf16 v[82:85], v[168:171], v[192:195], v[82:85]
	v_mfma_f32_16x16x32_bf16 v[70:73], v[160:163], v[200:203], v[70:73]
	v_mfma_f32_16x16x32_bf16 v[66:69], v[168:171], v[200:203], v[66:69]
	v_mfma_f32_16x16x32_bf16 v[118:121], v[164:167], v[180:183], v[118:121]
	v_mfma_f32_16x16x32_bf16 v[114:117], v[172:175], v[180:183], v[114:117]
	v_mfma_f32_16x16x32_bf16 v[102:105], v[164:167], v[188:191], v[102:105]
	v_mfma_f32_16x16x32_bf16 v[98:101], v[172:175], v[188:191], v[98:101]
	v_mfma_f32_16x16x32_bf16 v[86:89], v[164:167], v[196:199], v[86:89]
	v_mfma_f32_16x16x32_bf16 v[82:85], v[172:175], v[196:199], v[82:85]
	v_mfma_f32_16x16x32_bf16 v[70:73], v[164:167], v[204:207], v[70:73]
	v_mfma_f32_16x16x32_bf16 v[66:69], v[172:175], v[204:207], v[66:69]
	s_setprio 0
	s_barrier
; #define PG8_STAGE(bufoff, gbase, voff) do { _Pragma("unroll") for (int _i = 0; _i < 2; ++_i) \
;         __builtin_amdgcn_global_load_lds((const unsigned*)((const char*)(gbase) + (voff)[_i]), (PG8_LAS unsigned*)(lds + (bufoff) + ldsw + _i * 8192), 16, 0, 0); } while (0)
; #define PG8_LDA(dst, b, h) do { _Pragma("unroll") for (int m = 0; m < 4; ++m) _Pragma("unroll") for (int k = 0; k < 2; ++k) dst[m][k] = *(const PG8_LAS bf16x8*)(lds + PG8_SA(b, h) + aoff + m * 2048 + k * 1024); } while (0)
; #define PG8_MMA(ai, bj, At, Bt) do { __builtin_amdgcn_s_setprio(1); _Pragma("unroll") for (int m = 0; m < 4; ++m) _Pragma("unroll") for (int n = 0; n < 2; ++n) _Pragma("unroll") for (int k = 0; k < 2; ++k) \
;         acc[ai][bj][m][n] = __builtin_amdgcn_mfma_f32_16x16x32_bf16(Bt[n][k], At[m][k], acc[ai][bj][m][n], 0, 0, 0); __builtin_amdgcn_s_setprio(0); } while (0)
; #define PG8_WAIT_V(n) asm volatile("s_waitcnt vmcnt(" #n ")" ::: "memory")
; #define PG8_WAIT_L(n) asm volatile("s_waitcnt lgkmcnt(" #n ")" ::: "memory")
; #define PG8_BAR __builtin_amdgcn_s_barrier()
; #define PG8_SCHED __builtin_amdgcn_sched_barrier(0)
; template <class Epi, class Sched, bool ALIGN_EPI = false, bool SP2 = false>
; __device__ __forceinline__ void gemm_phase(PG8_LAS unsigned char* lds, const Gemm g, const Sched& S, const Epi& E, int wave0) {
;     ...
;             PG8_WAIT_V(8); PG8_WAIT_L(0); PG8_BAR; PG8_MMA(0, 0, At, B0); PG8_MMA(0, 1, At, B1); PG8_BAR; PG8_SCHED;
;             PG8_LDA(At, 1, 1); PG8_STAGE(PG8_SB(1, 0), b3, voffB); PG8_STAGE(PG8_SB(1, 1), b3 + hstep, voffB); PG8_STAGE(PG8_SA(1, 0), a3, voffA);
;             PG8_WAIT_V(8); PG8_WAIT_L(0); PG8_BAR; PG8_MMA(1, 0, At, B0); PG8_MMA(1, 1, At, B1); PG8_BAR; PG8_SCHED;
	s_add_i32 s36, s36, s52
	v_lshl_add_u64 v[208:209], v[208:209], 0, s[34:35]
	s_mov_b32 m0, s36
	ds_read_b128 v[176:179], v147 offset:49152
	ds_read_b128 v[180:183], v147 offset:50176
	ds_read_b128 v[184:187], v147 offset:51200
	ds_read_b128 v[188:191], v147 offset:52224
	ds_read_b128 v[192:195], v147 offset:53248
	ds_read_b128 v[196:199], v147 offset:54272
	ds_read_b128 v[200:203], v147 offset:55296
	ds_read_b128 v[204:207], v147 offset:56320
	global_load_lds_dwordx4 v[208:209], off
	s_add_i32 m0, s36, 0x2000
	s_add_u32 s28, s28, 0x40080
	v_lshl_add_u64 v[208:209], v[210:211], 0, s[34:35]
	s_addc_u32 s29, s29, 0
	s_add_i32 s36, s68, s52
	global_load_lds_dwordx4 v[208:209], off
	v_lshl_add_u64 v[208:209], s[28:29], 0, v[0:1]
	s_mov_b32 m0, s36
	s_nop 0
	global_load_lds_dwordx4 v[208:209], off
	v_lshl_add_u64 v[208:209], s[28:29], 0, v[130:131]
	s_add_i32 m0, s36, 0x2000
	s_nop 0
	global_load_lds_dwordx4 v[208:209], off
	v_lshl_add_u64 v[208:209], v[212:213], 0, s[34:35]
	s_mov_b32 m0, s59
	s_nop 0
	global_load_lds_dwordx4 v[208:209], off
	v_lshl_add_u64 v[208:209], v[214:215], 0, s[34:35]
	s_mov_b32 m0, s60
	s_nop 0
	global_load_lds_dwordx4 v[208:209], off
	s_waitcnt vmcnt(8)
	s_waitcnt lgkmcnt(0)
	s_barrier
	s_setprio 1
	s_waitcnt lgkmcnt(0)
	v_mfma_f32_16x16x32_bf16 v[58:61], v[140:143], v[176:179], v[58:61]
	v_mfma_f32_16x16x32_bf16 v[62:65], v[152:155], v[176:179], v[62:65]
	v_mfma_f32_16x16x32_bf16 v[42:45], v[140:143], v[184:187], v[42:45]
	v_mfma_f32_16x16x32_bf16 v[46:49], v[152:155], v[184:187], v[46:49]
	v_mfma_f32_16x16x32_bf16 v[26:29], v[140:143], v[192:195], v[26:29]
	v_mfma_f32_16x16x32_bf16 v[30:33], v[152:155], v[192:195], v[30:33]
	v_mfma_f32_16x16x32_bf16 v[10:13], v[140:143], v[200:203], v[10:13]
	v_mfma_f32_16x16x32_bf16 v[14:17], v[152:155], v[200:203], v[14:17]
	v_mfma_f32_16x16x32_bf16 v[58:61], v[148:151], v[180:183], v[58:61]
	v_mfma_f32_16x16x32_bf16 v[62:65], v[156:159], v[180:183], v[62:65]
	v_mfma_f32_16x16x32_bf16 v[42:45], v[148:151], v[188:191], v[42:45]
	v_mfma_f32_16x16x32_bf16 v[46:49], v[156:159], v[188:191], v[46:49]
	v_mfma_f32_16x16x32_bf16 v[26:29], v[148:151], v[196:199], v[26:29]
	v_mfma_f32_16x16x32_bf16 v[30:33], v[156:159], v[196:199], v[30:33]
	v_mfma_f32_16x16x32_bf16 v[10:13], v[148:151], v[204:207], v[10:13]
	v_mfma_f32_16x16x32_bf16 v[14:17], v[156:159], v[204:207], v[14:17]
	s_setprio 0
	s_setprio 1
	v_mfma_f32_16x16x32_bf16 v[54:57], v[160:163], v[176:179], v[54:57]
	v_mfma_f32_16x16x32_bf16 v[50:53], v[168:171], v[176:179], v[50:53]
	v_mfma_f32_16x16x32_bf16 v[38:41], v[160:163], v[184:187], v[38:41]
	v_mfma_f32_16x16x32_bf16 v[34:37], v[168:171], v[184:187], v[34:37]
	v_mfma_f32_16x16x32_bf16 v[22:25], v[160:163], v[192:195], v[22:25]
	v_mfma_f32_16x16x32_bf16 v[18:21], v[168:171], v[192:195], v[18:21]
	v_mfma_f32_16x16x32_bf16 v[6:9], v[160:163], v[200:203], v[6:9]
	v_mfma_f32_16x16x32_bf16 v[2:5], v[168:171], v[200:203], v[2:5]
	v_mfma_f32_16x16x32_bf16 v[54:57], v[164:167], v[180:183], v[54:57]
	v_mfma_f32_16x16x32_bf16 v[50:53], v[172:175], v[180:183], v[50:53]
	v_mfma_f32_16x16x32_bf16 v[38:41], v[164:167], v[188:191], v[38:41]
	v_mfma_f32_16x16x32_bf16 v[34:37], v[172:175], v[188:191], v[34:37]
	v_mfma_f32_16x16x32_bf16 v[22:25], v[164:167], v[196:199], v[22:25]
	v_mfma_f32_16x16x32_bf16 v[18:21], v[172:175], v[196:199], v[18:21]
	v_mfma_f32_16x16x32_bf16 v[6:9], v[164:167], v[204:207], v[6:9]
	v_mfma_f32_16x16x32_bf16 v[2:5], v[172:175], v[204:207], v[2:5]
	s_setprio 0
	s_add_i32 s67, s67, 2
	s_add_u32 s46, s46, 0x100
	s_addc_u32 s47, s47, 0
	s_add_u32 s65, s65, 0x100
	s_addc_u32 s66, s66, 0
	s_cmp_gt_u32 s67, 13
	s_barrier
	s_cbranch_scc0 .LBB0_997
	s_and_b64 vcc, exec, s[22:23]
	s_cbranch_vccz .LBB0_1000
	s_barrier

; #define PG8_STAGE(bufoff, gbase, voff) do { _Pragma("unroll") for (int _i = 0; _i < 2; ++_i) \
;         __builtin_amdgcn_global_load_lds((const unsigned*)((const char*)(gbase) + (voff)[_i]), (PG8_LAS unsigned*)(lds + (bufoff) + ldsw + _i * 8192), 16, 0, 0); } while (0)
; #define PG8_LDA(dst, b, h) do { _Pragma("unroll") for (int m = 0; m < 4; ++m) _Pragma("unroll") for (int k = 0; k < 2; ++k) dst[m][k] = *(const PG8_LAS bf16x8*)(lds + PG8_SA(b, h) + aoff + m * 2048 + k * 1024); } while (0)
; #define PG8_LDB(dst, b, h) do { _Pragma("unroll") for (int n = 0; n < 2; ++n) _Pragma("unroll") for (int k = 0; k < 2; ++k) dst[n][k] = *(const PG8_LAS bf16x8*)(lds + PG8_SB(b, h) + boff + n * 2048 + k * 1024); } while (0)
; #define PG8_MMA(ai, bj, At, Bt) do { __builtin_amdgcn_s_setprio(1); _Pragma("unroll") for (int m = 0; m < 4; ++m) _Pragma("unroll") for (int n = 0; n < 2; ++n) _Pragma("unroll") for (int k = 0; k < 2; ++k) \
;         acc[ai][bj][m][n] = __builtin_amdgcn_mfma_f32_16x16x32_bf16(Bt[n][k], At[m][k], acc[ai][bj][m][n], 0, 0, 0); __builtin_amdgcn_s_setprio(0); } while (0)
; #define PG8_WAIT_V(n) asm volatile("s_waitcnt vmcnt(" #n ")" ::: "memory")
; #define PG8_WAIT_L(n) asm volatile("s_waitcnt lgkmcnt(" #n ")" ::: "memory")
; #define PG8_BAR __builtin_amdgcn_s_barrier()
; #define PG8_SCHED __builtin_amdgcn_sched_barrier(0)
; template <class Epi, class Sched, bool ALIGN_EPI = false, bool SP2 = false>
; __device__ __forceinline__ void gemm_phase(PG8_LAS unsigned char* lds, const Gemm g, const Sched& S, const Epi& E, int wave0) {
;     ...
;             PG8_LDB(B0, 0, 0); PG8_LDB(B1, 0, 1); PG8_SCHED; PG8_LDA(At, 0, 0); PG8_STAGE(PG8_SA(1, 1), a1 + hstep, voffA);
;             PG8_WAIT_V(8); PG8_WAIT_L(0); PG8_BAR; PG8_MMA(0, 0, At, B0); PG8_MMA(0, 1, At, B1); PG8_BAR; PG8_SCHED;
;             PG8_LDA(At, 0, 1); PG8_STAGE(PG8_SB(0, 0), b2, voffB); PG8_STAGE(PG8_SB(0, 1), b2 + hstep, voffB); PG8_STAGE(PG8_SA(0, 0), a2, voffA);
;             PG8_WAIT_V(8); PG8_WAIT_L(0); PG8_BAR; PG8_MMA(1, 0, At, B0); PG8_MMA(1, 1, At, B1); PG8_BAR; PG8_SCHED;
.LBB0_1111:
	s_add_i32 s65, 0, 0x10000
	v_add_u32_e32 v154, s65, v148
	ds_read_b128 v[140:143], v154
	ds_read_b128 v[144:147], v154 offset:1024
	ds_read_b128 v[150:153], v154 offset:2048
	ds_read_b128 v[154:157], v154 offset:3072
	s_add_u32 s36, s28, 0xfffc0080
	s_addc_u32 s38, s29, -1
	s_cmp_eq_u32 s64, 12
	s_cselect_b32 s43, s23, s38
	s_cselect_b32 s42, s60, s36
	s_cselect_b32 s39, s21, s63
	s_cselect_b32 s38, s61, s62
	s_add_i32 s36, 0, 0x14000
	v_add_u32_e32 v170, s36, v148
	ds_read_b128 v[158:161], v170
	ds_read_b128 v[162:165], v170 offset:1024
	ds_read_b128 v[166:169], v170 offset:2048
	ds_read_b128 v[170:173], v170 offset:3072
	v_lshl_add_u64 v[206:207], s[28:29], 0, v[136:137]
	s_add_i32 m0, s47, 0xc000
	ds_read_b128 v[174:177], v149
	ds_read_b128 v[178:181], v149 offset:1024
	ds_read_b128 v[182:185], v149 offset:2048
	ds_read_b128 v[186:189], v149 offset:3072
	ds_read_b128 v[190:193], v149 offset:4096
	ds_read_b128 v[194:197], v149 offset:5120
	ds_read_b128 v[198:201], v149 offset:6144
	ds_read_b128 v[202:205], v149 offset:7168
	global_load_lds_dwordx4 v[206:207], off
	v_lshl_add_u64 v[206:207], s[28:29], 0, v[138:139]
	s_add_i32 m0, s47, 0xe000
	s_nop 0
	global_load_lds_dwordx4 v[206:207], off
	s_waitcnt vmcnt(8)
	s_waitcnt lgkmcnt(0)
	s_barrier
	s_setprio 1
	s_waitcnt lgkmcnt(0)
	v_mfma_f32_16x16x32_bf16 v[126:129], v[140:143], v[174:177], v[126:129]
	v_mfma_f32_16x16x32_bf16 v[122:125], v[150:153], v[174:177], v[122:125]
	v_mfma_f32_16x16x32_bf16 v[110:113], v[140:143], v[182:185], v[110:113]
	v_mfma_f32_16x16x32_bf16 v[106:109], v[150:153], v[182:185], v[106:109]
	v_mfma_f32_16x16x32_bf16 v[94:97], v[140:143], v[190:193], v[94:97]
	v_mfma_f32_16x16x32_bf16 v[90:93], v[150:153], v[190:193], v[90:93]
	v_mfma_f32_16x16x32_bf16 v[78:81], v[140:143], v[198:201], v[78:81]
	v_mfma_f32_16x16x32_bf16 v[74:77], v[150:153], v[198:201], v[74:77]
	v_mfma_f32_16x16x32_bf16 v[126:129], v[144:147], v[178:181], v[126:129]
	v_mfma_f32_16x16x32_bf16 v[122:125], v[154:157], v[178:181], v[122:125]
	v_mfma_f32_16x16x32_bf16 v[110:113], v[144:147], v[186:189], v[110:113]
	v_mfma_f32_16x16x32_bf16 v[106:109], v[154:157], v[186:189], v[106:109]
	v_mfma_f32_16x16x32_bf16 v[94:97], v[144:147], v[194:197], v[94:97]
	v_mfma_f32_16x16x32_bf16 v[90:93], v[154:157], v[194:197], v[90:93]
	v_mfma_f32_16x16x32_bf16 v[78:81], v[144:147], v[202:205], v[78:81]
	v_mfma_f32_16x16x32_bf16 v[74:77], v[154:157], v[202:205], v[74:77]
	s_setprio 0
	s_setprio 1
	v_mfma_f32_16x16x32_bf16 v[118:121], v[158:161], v[174:177], v[118:121]
	v_mfma_f32_16x16x32_bf16 v[114:117], v[166:169], v[174:177], v[114:117]
	v_mfma_f32_16x16x32_bf16 v[102:105], v[158:161], v[182:185], v[102:105]
	v_mfma_f32_16x16x32_bf16 v[98:101], v[166:169], v[182:185], v[98:101]
	v_mfma_f32_16x16x32_bf16 v[86:89], v[158:161], v[190:193], v[86:89]
	v_mfma_f32_16x16x32_bf16 v[82:85], v[166:169], v[190:193], v[82:85]
	v_mfma_f32_16x16x32_bf16 v[70:73], v[158:161], v[198:201], v[70:73]
	v_mfma_f32_16x16x32_bf16 v[66:69], v[166:169], v[198:201], v[66:69]
	v_mfma_f32_16x16x32_bf16 v[118:121], v[162:165], v[178:181], v[118:121]
	v_mfma_f32_16x16x32_bf16 v[114:117], v[170:173], v[178:181], v[114:117]
	v_mfma_f32_16x16x32_bf16 v[102:105], v[162:165], v[186:189], v[102:105]
	v_mfma_f32_16x16x32_bf16 v[98:101], v[170:173], v[186:189], v[98:101]
	v_mfma_f32_16x16x32_bf16 v[86:89], v[162:165], v[194:197], v[86:89]
	v_mfma_f32_16x16x32_bf16 v[82:85], v[170:173], v[194:197], v[82:85]
	v_mfma_f32_16x16x32_bf16 v[70:73], v[162:165], v[202:205], v[70:73]
	v_mfma_f32_16x16x32_bf16 v[66:69], v[170:173], v[202:205], v[66:69]
	s_setprio 0
	s_barrier
	s_add_i32 s65, s65, s46
	v_lshl_add_u64 v[206:207], s[38:39], 0, v[0:1]
	s_mov_b32 m0, s65
	ds_read_b128 v[174:177], v149 offset:16384
	ds_read_b128 v[178:181], v149 offset:17408
	ds_read_b128 v[182:185], v149 offset:18432
	ds_read_b128 v[186:189], v149 offset:19456
	ds_read_b128 v[190:193], v149 offset:20480
	ds_read_b128 v[194:197], v149 offset:21504
	ds_read_b128 v[198:201], v149 offset:22528
	ds_read_b128 v[202:205], v149 offset:23552
	global_load_lds_dwordx4 v[206:207], off
	s_add_i32 m0, s65, 0x2000
	s_add_u32 s66, s38, 0x40000
	v_lshl_add_u64 v[208:209], s[38:39], 0, v[130:131]
	s_addc_u32 s67, s39, 0
	s_add_i32 s36, s36, s46
	global_load_lds_dwordx4 v[208:209], off
	v_lshl_add_u64 v[210:211], s[66:67], 0, v[0:1]
	s_mov_b32 m0, s36
	v_lshl_add_u64 v[212:213], s[42:43], 0, v[132:133]
	global_load_lds_dwordx4 v[210:211], off
	v_lshl_add_u64 v[210:211], s[66:67], 0, v[130:131]
	s_add_i32 m0, s36, 0x2000
	s_nop 0
	global_load_lds_dwordx4 v[210:211], off
	v_lshl_add_u64 v[210:211], s[42:43], 0, v[134:135]
	s_mov_b32 m0, s47
	s_nop 0
	global_load_lds_dwordx4 v[210:211], off
	s_mov_b32 m0, s48
	s_nop 0
	global_load_lds_dwordx4 v[212:213], off
	s_waitcnt vmcnt(8)
	s_waitcnt lgkmcnt(0)
	s_barrier
; #define PG8_STAGE(bufoff, gbase, voff) do { _Pragma("unroll") for (int _i = 0; _i < 2; ++_i) \
;         __builtin_amdgcn_global_load_lds((const unsigned*)((const char*)(gbase) + (voff)[_i]), (PG8_LAS unsigned*)(lds + (bufoff) + ldsw + _i * 8192), 16, 0, 0); } while (0)
; #define PG8_LDA(dst, b, h) do { _Pragma("unroll") for (int m = 0; m < 4; ++m) _Pragma("unroll") for (int k = 0; k < 2; ++k) dst[m][k] = *(const PG8_LAS bf16x8*)(lds + PG8_SA(b, h) + aoff + m * 2048 + k * 1024); } while (0)
; #define PG8_LDB(dst, b, h) do { _Pragma("unroll") for (int n = 0; n < 2; ++n) _Pragma("unroll") for (int k = 0; k < 2; ++k) dst[n][k] = *(const PG8_LAS bf16x8*)(lds + PG8_SB(b, h) + boff + n * 2048 + k * 1024); } while (0)
; #define PG8_MMA(ai, bj, At, Bt) do { __builtin_amdgcn_s_setprio(1); _Pragma("unroll") for (int m = 0; m < 4; ++m) _Pragma("unroll") for (int n = 0; n < 2; ++n) _Pragma("unroll") for (int k = 0; k < 2; ++k) \
;         acc[ai][bj][m][n] = __builtin_amdgcn_mfma_f32_16x16x32_bf16(Bt[n][k], At[m][k], acc[ai][bj][m][n], 0, 0, 0); __builtin_amdgcn_s_setprio(0); } while (0)
; #define PG8_WAIT_V(n) asm volatile("s_waitcnt vmcnt(" #n ")" ::: "memory")
; #define PG8_WAIT_L(n) asm volatile("s_waitcnt lgkmcnt(" #n ")" ::: "memory")
; #define PG8_BAR __builtin_amdgcn_s_barrier()
; #define PG8_SCHED __builtin_amdgcn_sched_barrier(0)
; template <class Epi, class Sched, bool ALIGN_EPI = false, bool SP2 = false>
; __device__ __forceinline__ void gemm_phase(PG8_LAS unsigned char* lds, const Gemm g, const Sched& S, const Epi& E, int wave0) {
;     ...
;             PG8_WAIT_V(8); PG8_WAIT_L(0); PG8_BAR; PG8_MMA(1, 0, At, B0); PG8_MMA(1, 1, At, B1); PG8_BAR; PG8_SCHED;
;             PG8_LDB(B0, 1, 0); PG8_LDB(B1, 1, 1); PG8_SCHED; PG8_LDA(At, 1, 0); PG8_STAGE(PG8_SA(0, 1), a2 + hstep, voffA);
;             PG8_WAIT_V(8); PG8_WAIT_L(0); PG8_BAR; PG8_MMA(0, 0, At, B0); PG8_MMA(0, 1, At, B1); PG8_BAR; PG8_SCHED;
	s_setprio 1
	s_waitcnt lgkmcnt(0)
	v_mfma_f32_16x16x32_bf16 v[62:65], v[140:143], v[174:177], v[62:65]
	v_mfma_f32_16x16x32_bf16 v[58:61], v[150:153], v[174:177], v[58:61]
	v_mfma_f32_16x16x32_bf16 v[46:49], v[140:143], v[182:185], v[46:49]
	v_mfma_f32_16x16x32_bf16 v[42:45], v[150:153], v[182:185], v[42:45]
	v_mfma_f32_16x16x32_bf16 v[30:33], v[140:143], v[190:193], v[30:33]
	v_mfma_f32_16x16x32_bf16 v[26:29], v[150:153], v[190:193], v[26:29]
	v_mfma_f32_16x16x32_bf16 v[14:17], v[140:143], v[198:201], v[14:17]
	v_mfma_f32_16x16x32_bf16 v[10:13], v[150:153], v[198:201], v[10:13]
	v_mfma_f32_16x16x32_bf16 v[62:65], v[144:147], v[178:181], v[62:65]
	v_mfma_f32_16x16x32_bf16 v[58:61], v[154:157], v[178:181], v[58:61]
	v_mfma_f32_16x16x32_bf16 v[46:49], v[144:147], v[186:189], v[46:49]
	v_mfma_f32_16x16x32_bf16 v[42:45], v[154:157], v[186:189], v[42:45]
	v_mfma_f32_16x16x32_bf16 v[30:33], v[144:147], v[194:197], v[30:33]
	v_mfma_f32_16x16x32_bf16 v[26:29], v[154:157], v[194:197], v[26:29]
	v_mfma_f32_16x16x32_bf16 v[14:17], v[144:147], v[202:205], v[14:17]
	v_mfma_f32_16x16x32_bf16 v[10:13], v[154:157], v[202:205], v[10:13]
	s_setprio 0
	s_setprio 1
	v_mfma_f32_16x16x32_bf16 v[54:57], v[158:161], v[174:177], v[54:57]
	v_mfma_f32_16x16x32_bf16 v[50:53], v[166:169], v[174:177], v[50:53]
	v_mfma_f32_16x16x32_bf16 v[38:41], v[158:161], v[182:185], v[38:41]
	v_mfma_f32_16x16x32_bf16 v[34:37], v[166:169], v[182:185], v[34:37]
	v_mfma_f32_16x16x32_bf16 v[22:25], v[158:161], v[190:193], v[22:25]
	v_mfma_f32_16x16x32_bf16 v[18:21], v[166:169], v[190:193], v[18:21]
	v_mfma_f32_16x16x32_bf16 v[6:9], v[158:161], v[198:201], v[6:9]
	v_mfma_f32_16x16x32_bf16 v[2:5], v[166:169], v[198:201], v[2:5]
	v_mfma_f32_16x16x32_bf16 v[54:57], v[162:165], v[178:181], v[54:57]
	v_mfma_f32_16x16x32_bf16 v[50:53], v[170:173], v[178:181], v[50:53]
	v_mfma_f32_16x16x32_bf16 v[38:41], v[162:165], v[186:189], v[38:41]
	v_mfma_f32_16x16x32_bf16 v[34:37], v[170:173], v[186:189], v[34:37]
	v_mfma_f32_16x16x32_bf16 v[22:25], v[162:165], v[194:197], v[22:25]
	v_mfma_f32_16x16x32_bf16 v[18:21], v[170:173], v[194:197], v[18:21]
	v_mfma_f32_16x16x32_bf16 v[6:9], v[162:165], v[202:205], v[6:9]
	v_mfma_f32_16x16x32_bf16 v[2:5], v[170:173], v[202:205], v[2:5]
	s_setprio 0
	s_barrier
	s_add_i32 s36, 0, 0x18000
	s_add_i32 s65, 0, 0x1c000
	v_add_u32_e32 v154, s36, v148
	v_add_u32_e32 v170, s65, v148
	ds_read_b128 v[140:143], v154
	ds_read_b128 v[144:147], v154 offset:1024
	ds_read_b128 v[150:153], v154 offset:2048
	ds_read_b128 v[154:157], v154 offset:3072
	ds_read_b128 v[158:161], v170
	ds_read_b128 v[162:165], v170 offset:1024
	ds_read_b128 v[166:169], v170 offset:2048
	ds_read_b128 v[170:173], v170 offset:3072
	s_add_u32 s42, s42, 0x40000
	s_addc_u32 s43, s43, 0
	s_mov_b32 m0, s49
	v_lshl_add_u64 v[214:215], s[42:43], 0, v[134:135]
	ds_read_b128 v[174:177], v149 offset:32768
	ds_read_b128 v[178:181], v149 offset:33792
	ds_read_b128 v[182:185], v149 offset:34816
	ds_read_b128 v[186:189], v149 offset:35840
	ds_read_b128 v[190:193], v149 offset:36864
	ds_read_b128 v[194:197], v149 offset:37888
	ds_read_b128 v[198:201], v149 offset:38912
	ds_read_b128 v[202:205], v149 offset:39936
	global_load_lds_dwordx4 v[214:215], off
	v_lshl_add_u64 v[214:215], s[42:43], 0, v[132:133]
	s_mov_b32 m0, s50
	s_nop 0
	global_load_lds_dwordx4 v[214:215], off
	s_waitcnt vmcnt(8)
	s_waitcnt lgkmcnt(0)
	s_barrier
	s_setprio 1
	s_waitcnt lgkmcnt(0)
	v_mfma_f32_16x16x32_bf16 v[126:129], v[140:143], v[174:177], v[126:129]
	v_mfma_f32_16x16x32_bf16 v[122:125], v[150:153], v[174:177], v[122:125]
	v_mfma_f32_16x16x32_bf16 v[110:113], v[140:143], v[182:185], v[110:113]
	v_mfma_f32_16x16x32_bf16 v[106:109], v[150:153], v[182:185], v[106:109]
	v_mfma_f32_16x16x32_bf16 v[94:97], v[140:143], v[190:193], v[94:97]
	v_mfma_f32_16x16x32_bf16 v[90:93], v[150:153], v[190:193], v[90:93]
	v_mfma_f32_16x16x32_bf16 v[78:81], v[140:143], v[198:201], v[78:81]
	v_mfma_f32_16x16x32_bf16 v[74:77], v[150:153], v[198:201], v[74:77]
	v_mfma_f32_16x16x32_bf16 v[126:129], v[144:147], v[178:181], v[126:129]
	v_mfma_f32_16x16x32_bf16 v[122:125], v[154:157], v[178:181], v[122:125]
	v_mfma_f32_16x16x32_bf16 v[110:113], v[144:147], v[186:189], v[110:113]
	v_mfma_f32_16x16x32_bf16 v[106:109], v[154:157], v[186:189], v[106:109]
	v_mfma_f32_16x16x32_bf16 v[94:97], v[144:147], v[194:197], v[94:97]
	v_mfma_f32_16x16x32_bf16 v[90:93], v[154:157], v[194:197], v[90:93]
	v_mfma_f32_16x16x32_bf16 v[78:81], v[144:147], v[202:205], v[78:81]
	v_mfma_f32_16x16x32_bf16 v[74:77], v[154:157], v[202:205], v[74:77]
	s_setprio 0
	s_setprio 1
	v_mfma_f32_16x16x32_bf16 v[118:121], v[158:161], v[174:177], v[118:121]
	v_mfma_f32_16x16x32_bf16 v[114:117], v[166:169], v[174:177], v[114:117]
	v_mfma_f32_16x16x32_bf16 v[102:105], v[158:161], v[182:185], v[102:105]
	v_mfma_f32_16x16x32_bf16 v[98:101], v[166:169], v[182:185], v[98:101]
	v_mfma_f32_16x16x32_bf16 v[86:89], v[158:161], v[190:193], v[86:89]
	v_mfma_f32_16x16x32_bf16 v[82:85], v[166:169], v[190:193], v[82:85]
	v_mfma_f32_16x16x32_bf16 v[70:73], v[158:161], v[198:201], v[70:73]
	v_mfma_f32_16x16x32_bf16 v[66:69], v[166:169], v[198:201], v[66:69]
	v_mfma_f32_16x16x32_bf16 v[118:121], v[162:165], v[178:181], v[118:121]
	v_mfma_f32_16x16x32_bf16 v[114:117], v[170:173], v[178:181], v[114:117]
	v_mfma_f32_16x16x32_bf16 v[102:105], v[162:165], v[186:189], v[102:105]
	v_mfma_f32_16x16x32_bf16 v[98:101], v[170:173], v[186:189], v[98:101]
	v_mfma_f32_16x16x32_bf16 v[86:89], v[162:165], v[194:197], v[86:89]
	v_mfma_f32_16x16x32_bf16 v[82:85], v[170:173], v[194:197], v[82:85]
	v_mfma_f32_16x16x32_bf16 v[70:73], v[162:165], v[202:205], v[70:73]
	v_mfma_f32_16x16x32_bf16 v[66:69], v[170:173], v[202:205], v[66:69]
	s_setprio 0
	s_barrier
; #define PG8_STAGE(bufoff, gbase, voff) do { _Pragma("unroll") for (int _i = 0; _i < 2; ++_i) \
;         __builtin_amdgcn_global_load_lds((const unsigned*)((const char*)(gbase) + (voff)[_i]), (PG8_LAS unsigned*)(lds + (bufoff) + ldsw + _i * 8192), 16, 0, 0); } while (0)
; #define PG8_LDA(dst, b, h) do { _Pragma("unroll") for (int m = 0; m < 4; ++m) _Pragma("unroll") for (int k = 0; k < 2; ++k) dst[m][k] = *(const PG8_LAS bf16x8*)(lds + PG8_SA(b, h) + aoff + m * 2048 + k * 1024); } while (0)
; #define PG8_MMA(ai, bj, At, Bt) do { __builtin_amdgcn_s_setprio(1); _Pragma("unroll") for (int m = 0; m < 4; ++m) _Pragma("unroll") for (int n = 0; n < 2; ++n) _Pragma("unroll") for (int k = 0; k < 2; ++k) \
;         acc[ai][bj][m][n] = __builtin_amdgcn_mfma_f32_16x16x32_bf16(Bt[n][k], At[m][k], acc[ai][bj][m][n], 0, 0, 0); __builtin_amdgcn_s_setprio(0); } while (0)
; #define PG8_WAIT_V(n) asm volatile("s_waitcnt vmcnt(" #n ")" ::: "memory")
; #define PG8_WAIT_L(n) asm volatile("s_waitcnt lgkmcnt(" #n ")" ::: "memory")
; #define PG8_BAR __builtin_amdgcn_s_barrier()
; #define PG8_SCHED __builtin_amdgcn_sched_barrier(0)
; template <class Epi, class Sched, bool ALIGN_EPI = false, bool SP2 = false>
; __device__ __forceinline__ void gemm_phase(PG8_LAS unsigned char* lds, const Gemm g, const Sched& S, const Epi& E, int wave0) {
;     ...
;             PG8_WAIT_V(8); PG8_WAIT_L(0); PG8_BAR; PG8_MMA(0, 0, At, B0); PG8_MMA(0, 1, At, B1); PG8_BAR; PG8_SCHED;
;             PG8_LDA(At, 1, 1); PG8_STAGE(PG8_SB(1, 0), b3, voffB); PG8_STAGE(PG8_SB(1, 1), b3 + hstep, voffB); PG8_STAGE(PG8_SA(1, 0), a3, voffA);
;             PG8_WAIT_V(8); PG8_WAIT_L(0); PG8_BAR; PG8_MMA(1, 0, At, B0); PG8_MMA(1, 1, At, B1); PG8_BAR; PG8_SCHED;
	s_add_i32 s36, s36, s46
	v_lshl_add_u64 v[206:207], v[206:207], 0, s[34:35]
	s_mov_b32 m0, s36
	ds_read_b128 v[174:177], v149 offset:49152
	ds_read_b128 v[178:181], v149 offset:50176
	ds_read_b128 v[182:185], v149 offset:51200
	ds_read_b128 v[186:189], v149 offset:52224
	ds_read_b128 v[190:193], v149 offset:53248
	ds_read_b128 v[194:197], v149 offset:54272
	ds_read_b128 v[198:201], v149 offset:55296
	ds_read_b128 v[202:205], v149 offset:56320
	global_load_lds_dwordx4 v[206:207], off
	s_add_i32 m0, s36, 0x2000
	s_add_u32 s38, s38, 0x40080
	v_lshl_add_u64 v[206:207], v[208:209], 0, s[34:35]
	s_addc_u32 s39, s39, 0
	s_add_i32 s36, s65, s46
	global_load_lds_dwordx4 v[206:207], off
	v_lshl_add_u64 v[206:207], s[38:39], 0, v[0:1]
	s_mov_b32 m0, s36
	s_nop 0
	global_load_lds_dwordx4 v[206:207], off
	v_lshl_add_u64 v[206:207], s[38:39], 0, v[130:131]
	s_add_i32 m0, s36, 0x2000
	s_nop 0
	global_load_lds_dwordx4 v[206:207], off
	v_lshl_add_u64 v[206:207], v[210:211], 0, s[34:35]
	s_mov_b32 m0, s53
	s_nop 0
	global_load_lds_dwordx4 v[206:207], off
	v_lshl_add_u64 v[206:207], v[212:213], 0, s[34:35]
	s_mov_b32 m0, s54
	s_nop 0
	global_load_lds_dwordx4 v[206:207], off
	s_waitcnt vmcnt(8)
	s_waitcnt lgkmcnt(0)
	s_barrier
	s_setprio 1
	s_waitcnt lgkmcnt(0)
	v_mfma_f32_16x16x32_bf16 v[62:65], v[140:143], v[174:177], v[62:65]
	v_mfma_f32_16x16x32_bf16 v[58:61], v[150:153], v[174:177], v[58:61]
	v_mfma_f32_16x16x32_bf16 v[46:49], v[140:143], v[182:185], v[46:49]
	v_mfma_f32_16x16x32_bf16 v[42:45], v[150:153], v[182:185], v[42:45]
	v_mfma_f32_16x16x32_bf16 v[30:33], v[140:143], v[190:193], v[30:33]
	v_mfma_f32_16x16x32_bf16 v[26:29], v[150:153], v[190:193], v[26:29]
	v_mfma_f32_16x16x32_bf16 v[14:17], v[140:143], v[198:201], v[14:17]
	v_mfma_f32_16x16x32_bf16 v[10:13], v[150:153], v[198:201], v[10:13]
	v_mfma_f32_16x16x32_bf16 v[62:65], v[144:147], v[178:181], v[62:65]
	v_mfma_f32_16x16x32_bf16 v[58:61], v[154:157], v[178:181], v[58:61]
	v_mfma_f32_16x16x32_bf16 v[46:49], v[144:147], v[186:189], v[46:49]
	v_mfma_f32_16x16x32_bf16 v[42:45], v[154:157], v[186:189], v[42:45]
	v_mfma_f32_16x16x32_bf16 v[30:33], v[144:147], v[194:197], v[30:33]
	v_mfma_f32_16x16x32_bf16 v[26:29], v[154:157], v[194:197], v[26:29]
	v_mfma_f32_16x16x32_bf16 v[14:17], v[144:147], v[202:205], v[14:17]
	v_mfma_f32_16x16x32_bf16 v[10:13], v[154:157], v[202:205], v[10:13]
	s_setprio 0
	s_setprio 1
	v_mfma_f32_16x16x32_bf16 v[54:57], v[158:161], v[174:177], v[54:57]
	v_mfma_f32_16x16x32_bf16 v[50:53], v[166:169], v[174:177], v[50:53]
	v_mfma_f32_16x16x32_bf16 v[38:41], v[158:161], v[182:185], v[38:41]
	v_mfma_f32_16x16x32_bf16 v[34:37], v[166:169], v[182:185], v[34:37]
	v_mfma_f32_16x16x32_bf16 v[22:25], v[158:161], v[190:193], v[22:25]
	v_mfma_f32_16x16x32_bf16 v[18:21], v[166:169], v[190:193], v[18:21]
	v_mfma_f32_16x16x32_bf16 v[6:9], v[158:161], v[198:201], v[6:9]
	v_mfma_f32_16x16x32_bf16 v[2:5], v[166:169], v[198:201], v[2:5]
	v_mfma_f32_16x16x32_bf16 v[54:57], v[162:165], v[178:181], v[54:57]
	v_mfma_f32_16x16x32_bf16 v[50:53], v[170:173], v[178:181], v[50:53]
	v_mfma_f32_16x16x32_bf16 v[38:41], v[162:165], v[186:189], v[38:41]
	v_mfma_f32_16x16x32_bf16 v[34:37], v[170:173], v[186:189], v[34:37]
	v_mfma_f32_16x16x32_bf16 v[22:25], v[162:165], v[194:197], v[22:25]
	v_mfma_f32_16x16x32_bf16 v[18:21], v[170:173], v[194:197], v[18:21]
	v_mfma_f32_16x16x32_bf16 v[6:9], v[162:165], v[202:205], v[6:9]
	v_mfma_f32_16x16x32_bf16 v[2:5], v[170:173], v[202:205], v[2:5]
	s_setprio 0
	s_add_i32 s64, s64, 2
	s_add_u32 s28, s28, 0x100
	s_addc_u32 s29, s29, 0
	s_add_u32 s62, s62, 0x100
	s_addc_u32 s63, s63, 0
	s_cmp_gt_u32 s64, 13
	s_barrier
	s_cbranch_scc0 .LBB0_1111
	s_and_b64 vcc, exec, s[10:11]
	s_cbranch_vccz .LBB0_1114
	s_barrier

; #define PG8_STAGE(bufoff, gbase, voff) do { _Pragma("unroll") for (int _i = 0; _i < 2; ++_i) \
;         __builtin_amdgcn_global_load_lds((const unsigned*)((const char*)(gbase) + (voff)[_i]), (PG8_LAS unsigned*)(lds + (bufoff) + ldsw + _i * 8192), 16, 0, 0); } while (0)
; #define PG8_LDA(dst, b, h) do { _Pragma("unroll") for (int m = 0; m < 4; ++m) _Pragma("unroll") for (int k = 0; k < 2; ++k) dst[m][k] = *(const PG8_LAS bf16x8*)(lds + PG8_SA(b, h) + aoff + m * 2048 + k * 1024); } while (0)
; #define PG8_LDB(dst, b, h) do { _Pragma("unroll") for (int n = 0; n < 2; ++n) _Pragma("unroll") for (int k = 0; k < 2; ++k) dst[n][k] = *(const PG8_LAS bf16x8*)(lds + PG8_SB(b, h) + boff + n * 2048 + k * 1024); } while (0)
; #define PG8_MMA(ai, bj, At, Bt) do { __builtin_amdgcn_s_setprio(1); _Pragma("unroll") for (int m = 0; m < 4; ++m) _Pragma("unroll") for (int n = 0; n < 2; ++n) _Pragma("unroll") for (int k = 0; k < 2; ++k) \
;         acc[ai][bj][m][n] = __builtin_amdgcn_mfma_f32_16x16x32_bf16(Bt[n][k], At[m][k], acc[ai][bj][m][n], 0, 0, 0); __builtin_amdgcn_s_setprio(0); } while (0)
; #define PG8_WAIT_V(n) asm volatile("s_waitcnt vmcnt(" #n ")" ::: "memory")
; #define PG8_WAIT_L(n) asm volatile("s_waitcnt lgkmcnt(" #n ")" ::: "memory")
; #define PG8_BAR __builtin_amdgcn_s_barrier()
; #define PG8_SCHED __builtin_amdgcn_sched_barrier(0)
; template <class Epi, class Sched, bool ALIGN_EPI = false, bool SP2 = false>
; __device__ __forceinline__ void gemm_phase(PG8_LAS unsigned char* lds, const Gemm g, const Sched& S, const Epi& E, int wave0) {
;     ...
;             PG8_LDB(B0, 0, 0); PG8_LDB(B1, 0, 1); PG8_SCHED; PG8_LDA(At, 0, 0); PG8_STAGE(PG8_SA(1, 1), a1 + hstep, voffA);
;             PG8_WAIT_V(8); PG8_WAIT_L(0); PG8_BAR; PG8_MMA(0, 0, At, B0); PG8_MMA(0, 1, At, B1); PG8_BAR; PG8_SCHED;
;             PG8_LDA(At, 0, 1); PG8_STAGE(PG8_SB(0, 0), b2, voffB); PG8_STAGE(PG8_SB(0, 1), b2 + hstep, voffB); PG8_STAGE(PG8_SA(0, 0), a2, voffA);
;             PG8_WAIT_V(8); PG8_WAIT_L(0); PG8_BAR; PG8_MMA(1, 0, At, B0); PG8_MMA(1, 1, At, B1); PG8_BAR; PG8_SCHED;
.LBB0_1198:
	s_add_i32 s36, 0, 0x10000
	v_add_u32_e32 v144, s36, v147
	ds_read_b128 v[140:143], v144
	ds_read_b128 v[150:153], v144 offset:1024
	ds_read_b128 v[154:157], v144 offset:2048
	ds_read_b128 v[158:161], v144 offset:3072
	s_add_u32 s4, s6, 0xfff00080
	s_addc_u32 s5, s7, -1
	s_cmp_eq_u32 s63, 60
	s_cselect_b32 s29, s39, s5
	s_cselect_b32 s28, s47, s4
	s_cselect_b32 s5, s31, s62
	s_cselect_b32 s4, s60, s61
	s_add_i32 s66, 0, 0x14000
	v_add_u32_e32 v144, s66, v147
	ds_read_b128 v[162:165], v144
	ds_read_b128 v[166:169], v144 offset:1024
	ds_read_b128 v[170:173], v144 offset:2048
	ds_read_b128 v[174:177], v144 offset:3072
	v_lshl_add_u64 v[144:145], s[6:7], 0, v[136:137]
	s_add_i32 m0, s53, 0xc000
	ds_read_b128 v[178:181], v149
	ds_read_b128 v[182:185], v149 offset:1024
	ds_read_b128 v[186:189], v149 offset:2048
	ds_read_b128 v[190:193], v149 offset:3072
	ds_read_b128 v[194:197], v149 offset:4096
	ds_read_b128 v[198:201], v149 offset:5120
	ds_read_b128 v[202:205], v149 offset:6144
	ds_read_b128 v[206:209], v149 offset:7168
	global_load_lds_dwordx4 v[144:145], off
	v_lshl_add_u64 v[144:145], s[6:7], 0, v[138:139]
	s_add_i32 m0, s53, 0xe000
	s_nop 0
	global_load_lds_dwordx4 v[144:145], off
	s_waitcnt vmcnt(8)
	s_waitcnt lgkmcnt(0)
	s_barrier
	s_setprio 1
	s_waitcnt lgkmcnt(0)
	v_mfma_f32_16x16x32_bf16 v[126:129], v[140:143], v[178:181], v[126:129]
	v_mfma_f32_16x16x32_bf16 v[122:125], v[154:157], v[178:181], v[122:125]
	v_mfma_f32_16x16x32_bf16 v[110:113], v[140:143], v[186:189], v[110:113]
	v_mfma_f32_16x16x32_bf16 v[106:109], v[154:157], v[186:189], v[106:109]
	v_mfma_f32_16x16x32_bf16 v[94:97], v[140:143], v[194:197], v[94:97]
	v_mfma_f32_16x16x32_bf16 v[90:93], v[154:157], v[194:197], v[90:93]
	v_mfma_f32_16x16x32_bf16 v[78:81], v[140:143], v[202:205], v[78:81]
	v_mfma_f32_16x16x32_bf16 v[74:77], v[154:157], v[202:205], v[74:77]
	v_mfma_f32_16x16x32_bf16 v[126:129], v[150:153], v[182:185], v[126:129]
	v_mfma_f32_16x16x32_bf16 v[122:125], v[158:161], v[182:185], v[122:125]
	v_mfma_f32_16x16x32_bf16 v[110:113], v[150:153], v[190:193], v[110:113]
	v_mfma_f32_16x16x32_bf16 v[106:109], v[158:161], v[190:193], v[106:109]
	v_mfma_f32_16x16x32_bf16 v[94:97], v[150:153], v[198:201], v[94:97]
	v_mfma_f32_16x16x32_bf16 v[90:93], v[158:161], v[198:201], v[90:93]
	v_mfma_f32_16x16x32_bf16 v[78:81], v[150:153], v[206:209], v[78:81]
	v_mfma_f32_16x16x32_bf16 v[74:77], v[158:161], v[206:209], v[74:77]
	s_setprio 0
	s_setprio 1
	v_mfma_f32_16x16x32_bf16 v[118:121], v[162:165], v[178:181], v[118:121]
	v_mfma_f32_16x16x32_bf16 v[114:117], v[170:173], v[178:181], v[114:117]
	v_mfma_f32_16x16x32_bf16 v[102:105], v[162:165], v[186:189], v[102:105]
	v_mfma_f32_16x16x32_bf16 v[98:101], v[170:173], v[186:189], v[98:101]
	v_mfma_f32_16x16x32_bf16 v[86:89], v[162:165], v[194:197], v[86:89]
	v_mfma_f32_16x16x32_bf16 v[82:85], v[170:173], v[194:197], v[82:85]
	v_mfma_f32_16x16x32_bf16 v[70:73], v[162:165], v[202:205], v[70:73]
	v_mfma_f32_16x16x32_bf16 v[66:69], v[170:173], v[202:205], v[66:69]
	v_mfma_f32_16x16x32_bf16 v[118:121], v[166:169], v[182:185], v[118:121]
	v_mfma_f32_16x16x32_bf16 v[114:117], v[174:177], v[182:185], v[114:117]
	v_mfma_f32_16x16x32_bf16 v[102:105], v[166:169], v[190:193], v[102:105]
	v_mfma_f32_16x16x32_bf16 v[98:101], v[174:177], v[190:193], v[98:101]
	v_mfma_f32_16x16x32_bf16 v[86:89], v[166:169], v[198:201], v[86:89]
	v_mfma_f32_16x16x32_bf16 v[82:85], v[174:177], v[198:201], v[82:85]
	v_mfma_f32_16x16x32_bf16 v[70:73], v[166:169], v[206:209], v[70:73]
	v_mfma_f32_16x16x32_bf16 v[66:69], v[174:177], v[206:209], v[66:69]
	s_setprio 0
	s_barrier
	s_add_i32 s36, s36, s50
	v_lshl_add_u64 v[144:145], s[4:5], 0, v[0:1]
	s_mov_b32 m0, s36
	ds_read_b128 v[178:181], v149 offset:16384
	ds_read_b128 v[182:185], v149 offset:17408
	ds_read_b128 v[186:189], v149 offset:18432
	ds_read_b128 v[190:193], v149 offset:19456
	ds_read_b128 v[194:197], v149 offset:20480
	ds_read_b128 v[198:201], v149 offset:21504
	ds_read_b128 v[202:205], v149 offset:22528
	ds_read_b128 v[206:209], v149 offset:23552
	global_load_lds_dwordx4 v[144:145], off
	s_add_i32 m0, s36, 0x2000
	s_add_u32 s64, s4, 0x100000
	v_lshl_add_u64 v[210:211], s[4:5], 0, v[130:131]
	s_addc_u32 s65, s5, 0
	s_add_i32 s36, s66, s50
	global_load_lds_dwordx4 v[210:211], off
	v_lshl_add_u64 v[212:213], s[64:65], 0, v[0:1]
	s_mov_b32 m0, s36
	v_lshl_add_u64 v[214:215], s[28:29], 0, v[132:133]
	global_load_lds_dwordx4 v[212:213], off
	v_lshl_add_u64 v[212:213], s[64:65], 0, v[130:131]
	s_add_i32 m0, s36, 0x2000
	s_nop 0
	global_load_lds_dwordx4 v[212:213], off
	v_lshl_add_u64 v[212:213], s[28:29], 0, v[134:135]
	s_mov_b32 m0, s53
	s_nop 0
	global_load_lds_dwordx4 v[212:213], off
	s_mov_b32 m0, s54
	s_nop 0
	global_load_lds_dwordx4 v[214:215], off
	s_waitcnt vmcnt(8)
	s_waitcnt lgkmcnt(0)
	s_barrier
; #define PG8_STAGE(bufoff, gbase, voff) do { _Pragma("unroll") for (int _i = 0; _i < 2; ++_i) \
;         __builtin_amdgcn_global_load_lds((const unsigned*)((const char*)(gbase) + (voff)[_i]), (PG8_LAS unsigned*)(lds + (bufoff) + ldsw + _i * 8192), 16, 0, 0); } while (0)
; #define PG8_LDA(dst, b, h) do { _Pragma("unroll") for (int m = 0; m < 4; ++m) _Pragma("unroll") for (int k = 0; k < 2; ++k) dst[m][k] = *(const PG8_LAS bf16x8*)(lds + PG8_SA(b, h) + aoff + m * 2048 + k * 1024); } while (0)
; #define PG8_LDB(dst, b, h) do { _Pragma("unroll") for (int n = 0; n < 2; ++n) _Pragma("unroll") for (int k = 0; k < 2; ++k) dst[n][k] = *(const PG8_LAS bf16x8*)(lds + PG8_SB(b, h) + boff + n * 2048 + k * 1024); } while (0)
; #define PG8_MMA(ai, bj, At, Bt) do { __builtin_amdgcn_s_setprio(1); _Pragma("unroll") for (int m = 0; m < 4; ++m) _Pragma("unroll") for (int n = 0; n < 2; ++n) _Pragma("unroll") for (int k = 0; k < 2; ++k) \
;         acc[ai][bj][m][n] = __builtin_amdgcn_mfma_f32_16x16x32_bf16(Bt[n][k], At[m][k], acc[ai][bj][m][n], 0, 0, 0); __builtin_amdgcn_s_setprio(0); } while (0)
; #define PG8_WAIT_V(n) asm volatile("s_waitcnt vmcnt(" #n ")" ::: "memory")
; #define PG8_WAIT_L(n) asm volatile("s_waitcnt lgkmcnt(" #n ")" ::: "memory")
; #define PG8_BAR __builtin_amdgcn_s_barrier()
; #define PG8_SCHED __builtin_amdgcn_sched_barrier(0)
; template <class Epi, class Sched, bool ALIGN_EPI = false, bool SP2 = false>
; __device__ __forceinline__ void gemm_phase(PG8_LAS unsigned char* lds, const Gemm g, const Sched& S, const Epi& E, int wave0) {
;     ...
;             PG8_WAIT_V(8); PG8_WAIT_L(0); PG8_BAR; PG8_MMA(1, 0, At, B0); PG8_MMA(1, 1, At, B1); PG8_BAR; PG8_SCHED;
;             PG8_LDB(B0, 1, 0); PG8_LDB(B1, 1, 1); PG8_SCHED; PG8_LDA(At, 1, 0); PG8_STAGE(PG8_SA(0, 1), a2 + hstep, voffA);
;             PG8_WAIT_V(8); PG8_WAIT_L(0); PG8_BAR; PG8_MMA(0, 0, At, B0); PG8_MMA(0, 1, At, B1); PG8_BAR; PG8_SCHED;
	s_setprio 1
	s_waitcnt lgkmcnt(0)
	v_mfma_f32_16x16x32_bf16 v[58:61], v[140:143], v[178:181], v[58:61]
	v_mfma_f32_16x16x32_bf16 v[62:65], v[154:157], v[178:181], v[62:65]
	v_mfma_f32_16x16x32_bf16 v[42:45], v[140:143], v[186:189], v[42:45]
	v_mfma_f32_16x16x32_bf16 v[46:49], v[154:157], v[186:189], v[46:49]
	v_mfma_f32_16x16x32_bf16 v[26:29], v[140:143], v[194:197], v[26:29]
	v_mfma_f32_16x16x32_bf16 v[30:33], v[154:157], v[194:197], v[30:33]
	v_mfma_f32_16x16x32_bf16 v[10:13], v[140:143], v[202:205], v[10:13]
	v_mfma_f32_16x16x32_bf16 v[14:17], v[154:157], v[202:205], v[14:17]
	v_mfma_f32_16x16x32_bf16 v[58:61], v[150:153], v[182:185], v[58:61]
	v_mfma_f32_16x16x32_bf16 v[62:65], v[158:161], v[182:185], v[62:65]
	v_mfma_f32_16x16x32_bf16 v[42:45], v[150:153], v[190:193], v[42:45]
	v_mfma_f32_16x16x32_bf16 v[46:49], v[158:161], v[190:193], v[46:49]
	v_mfma_f32_16x16x32_bf16 v[26:29], v[150:153], v[198:201], v[26:29]
	v_mfma_f32_16x16x32_bf16 v[30:33], v[158:161], v[198:201], v[30:33]
	v_mfma_f32_16x16x32_bf16 v[10:13], v[150:153], v[206:209], v[10:13]
	v_mfma_f32_16x16x32_bf16 v[14:17], v[158:161], v[206:209], v[14:17]
	s_setprio 0
	s_setprio 1
	v_mfma_f32_16x16x32_bf16 v[54:57], v[162:165], v[178:181], v[54:57]
	v_mfma_f32_16x16x32_bf16 v[50:53], v[170:173], v[178:181], v[50:53]
	v_mfma_f32_16x16x32_bf16 v[38:41], v[162:165], v[186:189], v[38:41]
	v_mfma_f32_16x16x32_bf16 v[34:37], v[170:173], v[186:189], v[34:37]
	v_mfma_f32_16x16x32_bf16 v[22:25], v[162:165], v[194:197], v[22:25]
	v_mfma_f32_16x16x32_bf16 v[18:21], v[170:173], v[194:197], v[18:21]
	v_mfma_f32_16x16x32_bf16 v[6:9], v[162:165], v[202:205], v[6:9]
	v_mfma_f32_16x16x32_bf16 v[2:5], v[170:173], v[202:205], v[2:5]
	v_mfma_f32_16x16x32_bf16 v[54:57], v[166:169], v[182:185], v[54:57]
	v_mfma_f32_16x16x32_bf16 v[50:53], v[174:177], v[182:185], v[50:53]
	v_mfma_f32_16x16x32_bf16 v[38:41], v[166:169], v[190:193], v[38:41]
	v_mfma_f32_16x16x32_bf16 v[34:37], v[174:177], v[190:193], v[34:37]
	v_mfma_f32_16x16x32_bf16 v[22:25], v[166:169], v[198:201], v[22:25]
	v_mfma_f32_16x16x32_bf16 v[18:21], v[174:177], v[198:201], v[18:21]
	v_mfma_f32_16x16x32_bf16 v[6:9], v[166:169], v[206:209], v[6:9]
	v_mfma_f32_16x16x32_bf16 v[2:5], v[174:177], v[206:209], v[2:5]
	s_setprio 0
	s_barrier
	s_add_i32 s36, 0, 0x18000
	s_add_i32 s64, 0, 0x1c000
	v_add_u32_e32 v158, s36, v147
	v_add_u32_e32 v174, s64, v147
	ds_read_b128 v[140:143], v158
	ds_read_b128 v[150:153], v158 offset:1024
	ds_read_b128 v[154:157], v158 offset:2048
	ds_read_b128 v[158:161], v158 offset:3072
	ds_read_b128 v[162:165], v174
	ds_read_b128 v[166:169], v174 offset:1024
	ds_read_b128 v[170:173], v174 offset:2048
	ds_read_b128 v[174:177], v174 offset:3072
	s_add_u32 s28, s28, 0x100000
	s_addc_u32 s29, s29, 0
	s_mov_b32 m0, s55
	v_lshl_add_u64 v[216:217], s[28:29], 0, v[134:135]
	ds_read_b128 v[178:181], v149 offset:32768
	ds_read_b128 v[182:185], v149 offset:33792
	ds_read_b128 v[186:189], v149 offset:34816
	ds_read_b128 v[190:193], v149 offset:35840
	ds_read_b128 v[194:197], v149 offset:36864
	ds_read_b128 v[198:201], v149 offset:37888
	ds_read_b128 v[202:205], v149 offset:38912
	ds_read_b128 v[206:209], v149 offset:39936
	global_load_lds_dwordx4 v[216:217], off
	v_lshl_add_u64 v[216:217], s[28:29], 0, v[132:133]
	s_mov_b32 m0, s56
	s_nop 0
	global_load_lds_dwordx4 v[216:217], off
	s_waitcnt vmcnt(8)
	s_waitcnt lgkmcnt(0)
	s_barrier
	s_setprio 1
	s_waitcnt lgkmcnt(0)
	v_mfma_f32_16x16x32_bf16 v[126:129], v[140:143], v[178:181], v[126:129]
	v_mfma_f32_16x16x32_bf16 v[122:125], v[154:157], v[178:181], v[122:125]
	v_mfma_f32_16x16x32_bf16 v[110:113], v[140:143], v[186:189], v[110:113]
	v_mfma_f32_16x16x32_bf16 v[106:109], v[154:157], v[186:189], v[106:109]
	v_mfma_f32_16x16x32_bf16 v[94:97], v[140:143], v[194:197], v[94:97]
	v_mfma_f32_16x16x32_bf16 v[90:93], v[154:157], v[194:197], v[90:93]
	v_mfma_f32_16x16x32_bf16 v[78:81], v[140:143], v[202:205], v[78:81]
	v_mfma_f32_16x16x32_bf16 v[74:77], v[154:157], v[202:205], v[74:77]
	v_mfma_f32_16x16x32_bf16 v[126:129], v[150:153], v[182:185], v[126:129]
	v_mfma_f32_16x16x32_bf16 v[122:125], v[158:161], v[182:185], v[122:125]
	v_mfma_f32_16x16x32_bf16 v[110:113], v[150:153], v[190:193], v[110:113]
	v_mfma_f32_16x16x32_bf16 v[106:109], v[158:161], v[190:193], v[106:109]
	v_mfma_f32_16x16x32_bf16 v[94:97], v[150:153], v[198:201], v[94:97]
	v_mfma_f32_16x16x32_bf16 v[90:93], v[158:161], v[198:201], v[90:93]
	v_mfma_f32_16x16x32_bf16 v[78:81], v[150:153], v[206:209], v[78:81]
	v_mfma_f32_16x16x32_bf16 v[74:77], v[158:161], v[206:209], v[74:77]
	s_setprio 0
	s_setprio 1
	v_mfma_f32_16x16x32_bf16 v[118:121], v[162:165], v[178:181], v[118:121]
	v_mfma_f32_16x16x32_bf16 v[114:117], v[170:173], v[178:181], v[114:117]
	v_mfma_f32_16x16x32_bf16 v[102:105], v[162:165], v[186:189], v[102:105]
	v_mfma_f32_16x16x32_bf16 v[98:101], v[170:173], v[186:189], v[98:101]
	v_mfma_f32_16x16x32_bf16 v[86:89], v[162:165], v[194:197], v[86:89]
	v_mfma_f32_16x16x32_bf16 v[82:85], v[170:173], v[194:197], v[82:85]
	v_mfma_f32_16x16x32_bf16 v[70:73], v[162:165], v[202:205], v[70:73]
	v_mfma_f32_16x16x32_bf16 v[66:69], v[170:173], v[202:205], v[66:69]
	v_mfma_f32_16x16x32_bf16 v[118:121], v[166:169], v[182:185], v[118:121]
	v_mfma_f32_16x16x32_bf16 v[114:117], v[174:177], v[182:185], v[114:117]
	v_mfma_f32_16x16x32_bf16 v[102:105], v[166:169], v[190:193], v[102:105]
	v_mfma_f32_16x16x32_bf16 v[98:101], v[174:177], v[190:193], v[98:101]
	v_mfma_f32_16x16x32_bf16 v[86:89], v[166:169], v[198:201], v[86:89]
	v_mfma_f32_16x16x32_bf16 v[82:85], v[174:177], v[198:201], v[82:85]
	v_mfma_f32_16x16x32_bf16 v[70:73], v[166:169], v[206:209], v[70:73]
	v_mfma_f32_16x16x32_bf16 v[66:69], v[174:177], v[206:209], v[66:69]
	s_setprio 0
	s_barrier
; #define PG8_STAGE(bufoff, gbase, voff) do { _Pragma("unroll") for (int _i = 0; _i < 2; ++_i) \
;         __builtin_amdgcn_global_load_lds((const unsigned*)((const char*)(gbase) + (voff)[_i]), (PG8_LAS unsigned*)(lds + (bufoff) + ldsw + _i * 8192), 16, 0, 0); } while (0)
; #define PG8_LDA(dst, b, h) do { _Pragma("unroll") for (int m = 0; m < 4; ++m) _Pragma("unroll") for (int k = 0; k < 2; ++k) dst[m][k] = *(const PG8_LAS bf16x8*)(lds + PG8_SA(b, h) + aoff + m * 2048 + k * 1024); } while (0)
; #define PG8_LDB(dst, b, h) do { _Pragma("unroll") for (int n = 0; n < 2; ++n) _Pragma("unroll") for (int k = 0; k < 2; ++k) dst[n][k] = *(const PG8_LAS bf16x8*)(lds + PG8_SB(b, h) + boff + n * 2048 + k * 1024); } while (0)
; #define PG8_BAR __builtin_amdgcn_s_barrier()
; template <class Epi, class Sched, bool ALIGN_EPI = false, bool SP2 = false>
; __device__ __forceinline__ void gemm_phase(PG8_LAS unsigned char* lds, const Gemm g, const Sched& S, const Epi& E, int wave0) {
;     ...
;         for (int t = 0; t < nt; t += 2) {
;             const bool last = (t == nt - 2);
;             const char* a1 = cA + (size_t)(t + 1) * kstep;
;             const char* a2 = last ? nA : cA + (size_t)(t + 2) * kstep; const char* b2 = last ? nB : cB + (size_t)(t + 2) * kstep;
;             const char* a3 = a2 + kstep; const char* b3 = b2 + kstep;
;             if constexpr (SP2) {
;             PG8_LDB(B0, 0, 0); PG8_LDB(B1, 0, 1); PG8_SCHED; PG8_LDA(At, 0, 0); PG8_STAGE(PG8_SA(1, 1), a1 + hstep, voffA);
;             PG8_WAIT_V(8); PG8_WAIT_L(0); PG8_BAR; PG8_MMA(0, 0, At, B0); PG8_MMA(0, 1, At, B1); PG8_BAR; PG8_SCHED;
;             PG8_LDA(At, 0, 1); PG8_STAGE(PG8_SB(0, 0), b2, voffB); PG8_STAGE(PG8_SB(0, 1), b2 + hstep, voffB); PG8_STAGE(PG8_SA(0, 0), a2, voffA);
;             PG8_WAIT_V(8); PG8_WAIT_L(0); PG8_BAR; PG8_MMA(1, 0, At, B0); PG8_MMA(1, 1, At, B1); PG8_BAR; PG8_SCHED;
;             PG8_LDB(B0, 1, 0); PG8_LDB(B1, 1, 1); PG8_SCHED; PG8_LDA(At, 1, 0); PG8_STAGE(PG8_SA(0, 1), a2 + hstep, voffA);
;             PG8_WAIT_V(8); PG8_WAIT_L(0); PG8_BAR; PG8_MMA(0, 0, At, B0); PG8_MMA(0, 1, At, B1); PG8_BAR; PG8_SCHED;
;             PG8_LDA(At, 1, 1); PG8_STAGE(PG8_SB(1, 0), b3, voffB); PG8_STAGE(PG8_SB(1, 1), b3 + hstep, voffB); PG8_STAGE(PG8_SA(1, 0), a3, voffA);
;             PG8_WAIT_V(8); PG8_WAIT_L(0); PG8_BAR; PG8_MMA(1, 0, At, B0); PG8_MMA(1, 1, At, B1); PG8_BAR; PG8_SCHED;
	s_add_i32 s28, s36, s50
	v_lshl_add_u64 v[144:145], v[144:145], 0, s[34:35]
	s_mov_b32 m0, s28
	ds_read_b128 v[178:181], v149 offset:49152
	ds_read_b128 v[182:185], v149 offset:50176
	ds_read_b128 v[186:189], v149 offset:51200
	ds_read_b128 v[190:193], v149 offset:52224
	ds_read_b128 v[194:197], v149 offset:53248
	ds_read_b128 v[198:201], v149 offset:54272
	ds_read_b128 v[202:205], v149 offset:55296
	ds_read_b128 v[206:209], v149 offset:56320
	global_load_lds_dwordx4 v[144:145], off
	s_add_i32 m0, s28, 0x2000
	s_add_u32 s4, s4, 0x100080
	v_lshl_add_u64 v[144:145], v[210:211], 0, s[34:35]
	s_addc_u32 s5, s5, 0
	s_add_i32 s28, s64, s50
	global_load_lds_dwordx4 v[144:145], off
	v_lshl_add_u64 v[144:145], s[4:5], 0, v[0:1]
	s_mov_b32 m0, s28
	s_nop 0
	global_load_lds_dwordx4 v[144:145], off
	v_lshl_add_u64 v[144:145], s[4:5], 0, v[130:131]
	s_add_i32 m0, s28, 0x2000
	s_nop 0
	global_load_lds_dwordx4 v[144:145], off
	v_lshl_add_u64 v[144:145], v[212:213], 0, s[34:35]
	s_mov_b32 m0, s57
	s_nop 0
	global_load_lds_dwordx4 v[144:145], off
	v_lshl_add_u64 v[144:145], v[214:215], 0, s[34:35]
	s_mov_b32 m0, s58
	s_nop 0
	global_load_lds_dwordx4 v[144:145], off
	s_waitcnt vmcnt(8)
	s_waitcnt lgkmcnt(0)
	s_barrier
	s_setprio 1
	s_waitcnt lgkmcnt(0)
	v_mfma_f32_16x16x32_bf16 v[58:61], v[140:143], v[178:181], v[58:61]
	v_mfma_f32_16x16x32_bf16 v[62:65], v[154:157], v[178:181], v[62:65]
	v_mfma_f32_16x16x32_bf16 v[42:45], v[140:143], v[186:189], v[42:45]
	v_mfma_f32_16x16x32_bf16 v[46:49], v[154:157], v[186:189], v[46:49]
	v_mfma_f32_16x16x32_bf16 v[26:29], v[140:143], v[194:197], v[26:29]
	v_mfma_f32_16x16x32_bf16 v[30:33], v[154:157], v[194:197], v[30:33]
	v_mfma_f32_16x16x32_bf16 v[10:13], v[140:143], v[202:205], v[10:13]
	v_mfma_f32_16x16x32_bf16 v[14:17], v[154:157], v[202:205], v[14:17]
	v_mfma_f32_16x16x32_bf16 v[58:61], v[150:153], v[182:185], v[58:61]
	v_mfma_f32_16x16x32_bf16 v[62:65], v[158:161], v[182:185], v[62:65]
	v_mfma_f32_16x16x32_bf16 v[42:45], v[150:153], v[190:193], v[42:45]
	v_mfma_f32_16x16x32_bf16 v[46:49], v[158:161], v[190:193], v[46:49]
	v_mfma_f32_16x16x32_bf16 v[26:29], v[150:153], v[198:201], v[26:29]
	v_mfma_f32_16x16x32_bf16 v[30:33], v[158:161], v[198:201], v[30:33]
	v_mfma_f32_16x16x32_bf16 v[10:13], v[150:153], v[206:209], v[10:13]
	v_mfma_f32_16x16x32_bf16 v[14:17], v[158:161], v[206:209], v[14:17]
	s_setprio 0
	s_setprio 1
	v_mfma_f32_16x16x32_bf16 v[54:57], v[162:165], v[178:181], v[54:57]
	v_mfma_f32_16x16x32_bf16 v[50:53], v[170:173], v[178:181], v[50:53]
	v_mfma_f32_16x16x32_bf16 v[38:41], v[162:165], v[186:189], v[38:41]
	v_mfma_f32_16x16x32_bf16 v[34:37], v[170:173], v[186:189], v[34:37]
	v_mfma_f32_16x16x32_bf16 v[22:25], v[162:165], v[194:197], v[22:25]
	v_mfma_f32_16x16x32_bf16 v[18:21], v[170:173], v[194:197], v[18:21]
	v_mfma_f32_16x16x32_bf16 v[6:9], v[162:165], v[202:205], v[6:9]
	v_mfma_f32_16x16x32_bf16 v[2:5], v[170:173], v[202:205], v[2:5]
	v_mfma_f32_16x16x32_bf16 v[54:57], v[166:169], v[182:185], v[54:57]
	v_mfma_f32_16x16x32_bf16 v[50:53], v[174:177], v[182:185], v[50:53]
	v_mfma_f32_16x16x32_bf16 v[38:41], v[166:169], v[190:193], v[38:41]
	v_mfma_f32_16x16x32_bf16 v[34:37], v[174:177], v[190:193], v[34:37]
	v_mfma_f32_16x16x32_bf16 v[22:25], v[166:169], v[198:201], v[22:25]
	v_mfma_f32_16x16x32_bf16 v[18:21], v[174:177], v[198:201], v[18:21]
	v_mfma_f32_16x16x32_bf16 v[6:9], v[166:169], v[206:209], v[6:9]
	v_mfma_f32_16x16x32_bf16 v[2:5], v[174:177], v[206:209], v[2:5]
	s_setprio 0
	s_add_i32 s63, s63, 2
	s_add_u32 s6, s6, 0x100
	s_addc_u32 s7, s7, 0
	s_add_u32 s61, s61, 0x100
	s_addc_u32 s62, s62, 0
	s_cmp_gt_u32 s63, 61
	s_barrier
	s_cbranch_scc0 .LBB0_1198
	s_and_b64 vcc, exec, s[24:25]
	s_cbranch_vccz .LBB0_1201
	s_barrier
